# v58 + barrier-edge trimming: waves 4-7 raise their priority in front of the barrier (first MFMA directly behind the release), waves 0-3 reset theirs behind the barrier
# speedup vs baseline: 1.0093x; 1.0093x over previous
; #define PG8_STAGE(bufoff, gbase, voff) do { _Pragma("unroll") for (int _i = 0; _i < 2; ++_i) \
;         __builtin_amdgcn_global_load_lds((const unsigned*)((const char*)(gbase) + (voff)[_i]), (PG8_LAS unsigned*)(lds + (bufoff) + ldsw + _i * 8192), 16, 0, 0); } while (0)
; #define PG8_LDA(dst, b, h) do { _Pragma("unroll") for (int m = 0; m < 4; ++m) _Pragma("unroll") for (int k = 0; k < 2; ++k) dst[m][k] = *(const PG8_LAS bf16x8*)(lds + PG8_SA(b, h) + aoff + m * 2048 + k * 1024); } while (0)
; #define PG8_LDB(dst, b, h) do { _Pragma("unroll") for (int n = 0; n < 2; ++n) _Pragma("unroll") for (int k = 0; k < 2; ++k) dst[n][k] = *(const PG8_LAS bf16x8*)(lds + PG8_SB(b, h) + boff + n * 2048 + k * 1024); } while (0)
; #define PG8_MMA(ai, bj, At, Bt) do { __builtin_amdgcn_s_setprio(1); _Pragma("unroll") for (int m = 0; m < 4; ++m) _Pragma("unroll") for (int n = 0; n < 2; ++n) _Pragma("unroll") for (int k = 0; k < 2; ++k) \
;         acc[ai][bj][m][n] = __builtin_amdgcn_mfma_f32_16x16x32_bf16(Bt[n][k], At[m][k], acc[ai][bj][m][n], 0, 0, 0); __builtin_amdgcn_s_setprio(0); } while (0)
; #define PG8_BAR __builtin_amdgcn_s_barrier()
; template <class Epi, class Sched, bool ALIGN_EPI = false, bool SP2 = false>
; __device__ __forceinline__ void gemm_phase(PG8_LAS unsigned char* lds, const Gemm g, const Sched& S, const Epi& E) {
;     ...
;             const bool last = (t == nt - 2);
;             const char* a1 = cA + (size_t)(t + 1) * kstep;
;             const char* a2 = last ? nA : cA + (size_t)(t + 2) * kstep; const char* b2 = last ? nB : cB + (size_t)(t + 2) * kstep;
;             const char* a3 = a2 + kstep; const char* b3 = b2 + kstep;
;             if (last && has_next) S.a_ready(nxt);
;             if constexpr (Epi::MIDK) { if (t == (nt >> 1)) { E.midk(acc, wr, fr); asm volatile("s_waitcnt lgkmcnt(0)" ::: "memory"); } }
;             if constexpr (SP2) {
;             PG8_LDB(B0, 0, 0); PG8_LDB(B1, 0, 1); PG8_SCHED; PG8_LDA(At, 0, 0); PG8_STAGE(PG8_SA(1, 1), a1 + hstep, voffA);
;             PG8_WAIT_V(8); PG8_WAIT_L(0); PG8_BAR; PG8_MMA(0, 0, At, B0); PG8_MMA(0, 1, At, B1); PG8_BAR; PG8_SCHED;
;             PG8_LDA(At, 0, 1); PG8_STAGE(PG8_SB(0, 0), b2, voffB); PG8_STAGE(PG8_SB(0, 1), b2 + hstep, voffB); PG8_STAGE(PG8_SA(0, 0), a2, voffA);
;             PG8_WAIT_V(8); PG8_WAIT_L(0); PG8_BAR; PG8_MMA(1, 0, At, B0); PG8_MMA(1, 1, At, B1); PG8_BAR; PG8_SCHED;
.LBB0_349:
	ds_read_b128 v[150:153], v169
	ds_read_b128 v[154:157], v169 offset:1024
	ds_read_b128 v[158:161], v169 offset:2048
	ds_read_b128 v[162:165], v169 offset:3072
	ds_read_b128 v[174:177], v170
	ds_read_b128 v[178:181], v170 offset:1024
	ds_read_b128 v[182:185], v170 offset:2048
	ds_read_b128 v[186:189], v170 offset:3072
	s_add_u32 s0, s88, 0xfff00080
	s_addc_u32 s1, s89, -1
	s_cmp_eq_u32 s23, 60
	s_cselect_b32 s93, s51, s1
	s_cselect_b32 s92, s50, s0
	s_cselect_b32 s91, s53, s21
	s_cselect_b32 s90, s52, s9
	ds_read_b128 v[190:193], v171
	ds_read_b128 v[196:199], v171 offset:1024
	ds_read_b128 v[200:203], v171 offset:2048
	ds_read_b128 v[204:207], v171 offset:3072
	ds_read_b128 v[208:211], v171 offset:4096
	ds_read_b128 v[212:215], v171 offset:5120
	ds_read_b128 v[220:223], v171 offset:6144
	ds_read_b128 v[224:227], v171 offset:7168
	s_add_u32 s0, s88, 0xfff00000
	s_addc_u32 s1, s89, -1
	s_add_i32 m0, s27, 0x8000
	s_nop 0
	global_load_lds_dwordx4 v134, s[0:1]
	s_add_i32 m0, s27, 0xa000
	s_nop 0
	global_load_lds_dwordx4 v138, s[0:1]
	s_add_i32 m0, s27, 0xc000
	s_nop 0
	global_load_lds_dwordx4 v134, s[88:89]
	s_add_i32 m0, s27, 0xe000
	s_nop 0
	global_load_lds_dwordx4 v138, s[88:89]
	s_waitcnt lgkmcnt(0)
	s_setprio 1
	v_mfma_f32_16x16x32_bf16 v[38:41], v[150:153], v[190:193], v[38:41]
	v_mfma_f32_16x16x32_bf16 v[38:41], v[154:157], v[196:199], v[38:41]
	v_mfma_f32_16x16x32_bf16 v[30:33], v[158:161], v[190:193], v[30:33]
	v_mfma_f32_16x16x32_bf16 v[30:33], v[162:165], v[196:199], v[30:33]
	v_mfma_f32_16x16x32_bf16 v[50:53], v[174:177], v[190:193], v[50:53]
	v_mfma_f32_16x16x32_bf16 v[50:53], v[178:181], v[196:199], v[50:53]
	v_mfma_f32_16x16x32_bf16 v[46:49], v[182:185], v[190:193], v[46:49]
	v_mfma_f32_16x16x32_bf16 v[46:49], v[186:189], v[196:199], v[46:49]
	v_mfma_f32_16x16x32_bf16 v[118:121], v[182:185], v[200:203], v[118:121]
	v_mfma_f32_16x16x32_bf16 v[118:121], v[186:189], v[204:207], v[118:121]
	v_mfma_f32_16x16x32_bf16 v[122:125], v[174:177], v[200:203], v[122:125]
	v_mfma_f32_16x16x32_bf16 v[122:125], v[178:181], v[204:207], v[122:125]
	v_mfma_f32_16x16x32_bf16 v[126:129], v[158:161], v[200:203], v[126:129]
	v_mfma_f32_16x16x32_bf16 v[126:129], v[162:165], v[204:207], v[126:129]
	v_mfma_f32_16x16x32_bf16 v[130:133], v[150:153], v[200:203], v[130:133]
	v_mfma_f32_16x16x32_bf16 v[130:133], v[154:157], v[204:207], v[130:133]
	v_mfma_f32_16x16x32_bf16 v[114:117], v[150:153], v[208:211], v[114:117]
	v_mfma_f32_16x16x32_bf16 v[114:117], v[154:157], v[212:215], v[114:117]
	v_mfma_f32_16x16x32_bf16 v[110:113], v[158:161], v[208:211], v[110:113]
	v_mfma_f32_16x16x32_bf16 v[110:113], v[162:165], v[212:215], v[110:113]
	v_mfma_f32_16x16x32_bf16 v[106:109], v[174:177], v[208:211], v[106:109]
	v_mfma_f32_16x16x32_bf16 v[106:109], v[178:181], v[212:215], v[106:109]
	v_mfma_f32_16x16x32_bf16 v[102:105], v[182:185], v[208:211], v[102:105]
	v_mfma_f32_16x16x32_bf16 v[102:105], v[186:189], v[212:215], v[102:105]
	v_mfma_f32_16x16x32_bf16 v[86:89], v[182:185], v[220:223], v[86:89]
	v_mfma_f32_16x16x32_bf16 v[86:89], v[186:189], v[224:227], v[86:89]
	v_mfma_f32_16x16x32_bf16 v[90:93], v[174:177], v[220:223], v[90:93]
	v_mfma_f32_16x16x32_bf16 v[90:93], v[178:181], v[224:227], v[90:93]
	v_mfma_f32_16x16x32_bf16 v[94:97], v[158:161], v[220:223], v[94:97]
	v_mfma_f32_16x16x32_bf16 v[94:97], v[162:165], v[224:227], v[94:97]
	v_mfma_f32_16x16x32_bf16 v[98:101], v[150:153], v[220:223], v[98:101]
	v_mfma_f32_16x16x32_bf16 v[98:101], v[154:157], v[224:227], v[98:101]
	s_waitcnt vmcnt(8)
	s_barrier
	s_setprio 0
	ds_read_b128 v[190:193], v171 offset:16384
	ds_read_b128 v[196:199], v171 offset:17408
	ds_read_b128 v[200:203], v171 offset:18432
	ds_read_b128 v[204:207], v171 offset:19456
	ds_read_b128 v[208:211], v171 offset:20480
	ds_read_b128 v[212:215], v171 offset:21504
	ds_read_b128 v[220:223], v171 offset:22528
	ds_read_b128 v[224:227], v171 offset:23552
	s_add_u32 vcc_lo, s90, 0x100000
	s_addc_u32 vcc_hi, s91, 0
	s_add_i32 m0, s27, 0x10000
	s_nop 0
	global_load_lds_dwordx4 v136, s[90:91]
	s_add_i32 m0, s27, 0x12000
	s_nop 0
	global_load_lds_dwordx4 v140, s[90:91]
	s_add_i32 m0, s27, 0x14000
	s_nop 0
	global_load_lds_dwordx4 v136, vcc
	s_add_i32 m0, s27, 0x16000
	s_nop 0
	global_load_lds_dwordx4 v140, vcc
	s_waitcnt lgkmcnt(0)
	s_setprio 1
	v_mfma_f32_16x16x32_bf16 v[82:85], v[150:153], v[190:193], v[82:85]
	v_mfma_f32_16x16x32_bf16 v[82:85], v[154:157], v[196:199], v[82:85]
	v_mfma_f32_16x16x32_bf16 v[78:81], v[158:161], v[190:193], v[78:81]
	v_mfma_f32_16x16x32_bf16 v[78:81], v[162:165], v[196:199], v[78:81]
	v_mfma_f32_16x16x32_bf16 v[74:77], v[174:177], v[190:193], v[74:77]
	v_mfma_f32_16x16x32_bf16 v[74:77], v[178:181], v[196:199], v[74:77]
	v_mfma_f32_16x16x32_bf16 v[70:73], v[182:185], v[190:193], v[70:73]
	v_mfma_f32_16x16x32_bf16 v[70:73], v[186:189], v[196:199], v[70:73]
	v_mfma_f32_16x16x32_bf16 v[54:57], v[182:185], v[200:203], v[54:57]
	v_mfma_f32_16x16x32_bf16 v[54:57], v[186:189], v[204:207], v[54:57]
	v_mfma_f32_16x16x32_bf16 v[58:61], v[174:177], v[200:203], v[58:61]
	v_mfma_f32_16x16x32_bf16 v[58:61], v[178:181], v[204:207], v[58:61]
	v_mfma_f32_16x16x32_bf16 v[62:65], v[158:161], v[200:203], v[62:65]
	v_mfma_f32_16x16x32_bf16 v[62:65], v[162:165], v[204:207], v[62:65]
	v_mfma_f32_16x16x32_bf16 v[66:69], v[150:153], v[200:203], v[66:69]
	v_mfma_f32_16x16x32_bf16 v[66:69], v[154:157], v[204:207], v[66:69]
	v_mfma_f32_16x16x32_bf16 v[42:45], v[150:153], v[208:211], v[42:45]
	v_mfma_f32_16x16x32_bf16 v[42:45], v[154:157], v[212:215], v[42:45]
	v_mfma_f32_16x16x32_bf16 v[34:37], v[158:161], v[208:211], v[34:37]
	v_mfma_f32_16x16x32_bf16 v[34:37], v[162:165], v[212:215], v[34:37]
	v_mfma_f32_16x16x32_bf16 v[26:29], v[174:177], v[208:211], v[26:29]
	v_mfma_f32_16x16x32_bf16 v[26:29], v[178:181], v[212:215], v[26:29]
	v_mfma_f32_16x16x32_bf16 v[22:25], v[182:185], v[208:211], v[22:25]
	v_mfma_f32_16x16x32_bf16 v[22:25], v[186:189], v[212:215], v[22:25]
	v_mfma_f32_16x16x32_bf16 v[4:7], v[182:185], v[220:223], v[6:9]
	v_mfma_f32_16x16x32_bf16 v[4:7], v[186:189], v[224:227], v[4:7]
	v_mfma_f32_16x16x32_bf16 v[10:13], v[174:177], v[220:223], v[10:13]
	v_mfma_f32_16x16x32_bf16 v[10:13], v[178:181], v[224:227], v[10:13]
	v_mfma_f32_16x16x32_bf16 v[14:17], v[158:161], v[220:223], v[14:17]
	v_mfma_f32_16x16x32_bf16 v[14:17], v[162:165], v[224:227], v[14:17]
	v_mfma_f32_16x16x32_bf16 v[18:21], v[150:153], v[220:223], v[18:21]
	v_mfma_f32_16x16x32_bf16 v[18:21], v[154:157], v[224:227], v[18:21]
	s_waitcnt vmcnt(6)
	s_barrier
; #define PG8_STAGE(bufoff, gbase, voff) do { _Pragma("unroll") for (int _i = 0; _i < 2; ++_i) \
;         __builtin_amdgcn_global_load_lds((const unsigned*)((const char*)(gbase) + (voff)[_i]), (PG8_LAS unsigned*)(lds + (bufoff) + ldsw + _i * 8192), 16, 0, 0); } while (0)
; #define PG8_LDA(dst, b, h) do { _Pragma("unroll") for (int m = 0; m < 4; ++m) _Pragma("unroll") for (int k = 0; k < 2; ++k) dst[m][k] = *(const PG8_LAS bf16x8*)(lds + PG8_SA(b, h) + aoff + m * 2048 + k * 1024); } while (0)
; #define PG8_WAIT_V(n) asm volatile("s_waitcnt vmcnt(" #n ")" ::: "memory")
; template <class Epi, class Sched, bool ALIGN_EPI = false, bool SP2 = false>
; __device__ __forceinline__ void gemm_phase(PG8_LAS unsigned char* lds, const Gemm g, const Sched& S, const Epi& E) {
;     ...
;         for (int t = 0; t < nt; t += 2) {
;             const bool last = (t == nt - 2);
;             const char* a1 = cA + (size_t)(t + 1) * kstep;
;             const char* a2 = last ? nA : cA + (size_t)(t + 2) * kstep; const char* b2 = last ? nB : cB + (size_t)(t + 2) * kstep;
;             const char* a3 = a2 + kstep; const char* b3 = b2 + kstep;
;             if (last && has_next) S.a_ready(nxt);
;             if constexpr (Epi::MIDK) { if (t == (nt >> 1)) { E.midk(acc, wr, fr); asm volatile("s_waitcnt lgkmcnt(0)" ::: "memory"); } }
;             if constexpr (SP2) {
;             PG8_LDB(B0, 0, 0); PG8_LDB(B1, 0, 1); PG8_SCHED; PG8_LDA(At, 0, 0); PG8_STAGE(PG8_SA(1, 1), a1 + hstep, voffA);
;             PG8_WAIT_V(8); PG8_WAIT_L(0); PG8_BAR; PG8_MMA(0, 0, At, B0); PG8_MMA(0, 1, At, B1); PG8_BAR; PG8_SCHED;
;             PG8_LDA(At, 0, 1); PG8_STAGE(PG8_SB(0, 0), b2, voffB); PG8_STAGE(PG8_SB(0, 1), b2 + hstep, voffB); PG8_STAGE(PG8_SA(0, 0), a2, voffA);
;             PG8_WAIT_V(8); PG8_WAIT_L(0); PG8_BAR; PG8_MMA(1, 0, At, B0); PG8_MMA(1, 1, At, B1); PG8_BAR; PG8_SCHED;
;             PG8_LDB(B0, 1, 0); PG8_LDB(B1, 1, 1); PG8_SCHED; PG8_LDA(At, 1, 0); PG8_STAGE(PG8_SA(0, 1), a2 + hstep, voffA);
;             PG8_WAIT_V(8); PG8_WAIT_L(0); PG8_BAR; PG8_MMA(0, 0, At, B0); PG8_MMA(0, 1, At, B1); PG8_BAR; PG8_SCHED;
;             PG8_LDA(At, 1, 1); PG8_STAGE(PG8_SB(1, 0), b3, voffB); PG8_STAGE(PG8_SB(1, 1), b3 + hstep, voffB); PG8_STAGE(PG8_SA(1, 0), a3, voffA);
;             PG8_WAIT_V(8); PG8_WAIT_L(0); PG8_BAR; PG8_MMA(1, 0, At, B0); PG8_MMA(1, 1, At, B1); PG8_BAR; PG8_SCHED;
	s_setprio 0
	s_add_i32 s0, 0, 0x18000
	v_add_u32_e32 v3, s0, v167
	s_add_i32 s1, 0, 0x1c000
	ds_read_b128 v[150:153], v3
	ds_read_b128 v[154:157], v3 offset:1024
	ds_read_b128 v[158:161], v3 offset:2048
	ds_read_b128 v[162:165], v3 offset:3072
	v_add_u32_e32 v3, s1, v167
	ds_read_b128 v[174:177], v3
	ds_read_b128 v[178:181], v3 offset:1024
	ds_read_b128 v[182:185], v3 offset:2048
	ds_read_b128 v[186:189], v3 offset:3072
	ds_read_b128 v[190:193], v171 offset:32768
	ds_read_b128 v[196:199], v171 offset:33792
	ds_read_b128 v[200:203], v171 offset:34816
	ds_read_b128 v[204:207], v171 offset:35840
	ds_read_b128 v[208:211], v171 offset:36864
	ds_read_b128 v[212:215], v171 offset:37888
	ds_read_b128 v[220:223], v171 offset:38912
	ds_read_b128 v[224:227], v171 offset:39936
	s_add_u32 vcc_lo, s92, 0x100000
	s_addc_u32 vcc_hi, s93, 0
	s_mov_b32 m0, s27
	s_nop 0
	global_load_lds_dwordx4 v134, s[92:93]
	s_add_i32 m0, s27, 0x2000
	s_nop 0
	global_load_lds_dwordx4 v138, s[92:93]
	s_add_i32 m0, s27, 0x4000
	s_nop 0
	global_load_lds_dwordx4 v134, vcc
	s_add_i32 m0, s27, 0x6000
	s_nop 0
	global_load_lds_dwordx4 v138, vcc
	s_waitcnt lgkmcnt(0)
	s_setprio 1
	v_mfma_f32_16x16x32_bf16 v[38:41], v[150:153], v[190:193], v[38:41]
	v_mfma_f32_16x16x32_bf16 v[38:41], v[154:157], v[196:199], v[38:41]
	v_mfma_f32_16x16x32_bf16 v[30:33], v[158:161], v[190:193], v[30:33]
	v_mfma_f32_16x16x32_bf16 v[30:33], v[162:165], v[196:199], v[30:33]
	v_mfma_f32_16x16x32_bf16 v[50:53], v[174:177], v[190:193], v[50:53]
	v_mfma_f32_16x16x32_bf16 v[50:53], v[178:181], v[196:199], v[50:53]
	v_mfma_f32_16x16x32_bf16 v[46:49], v[182:185], v[190:193], v[46:49]
	v_mfma_f32_16x16x32_bf16 v[46:49], v[186:189], v[196:199], v[46:49]
	v_mfma_f32_16x16x32_bf16 v[118:121], v[182:185], v[200:203], v[118:121]
	v_mfma_f32_16x16x32_bf16 v[118:121], v[186:189], v[204:207], v[118:121]
	v_mfma_f32_16x16x32_bf16 v[122:125], v[174:177], v[200:203], v[122:125]
	v_mfma_f32_16x16x32_bf16 v[122:125], v[178:181], v[204:207], v[122:125]
	v_mfma_f32_16x16x32_bf16 v[126:129], v[158:161], v[200:203], v[126:129]
	v_mfma_f32_16x16x32_bf16 v[126:129], v[162:165], v[204:207], v[126:129]
	v_mfma_f32_16x16x32_bf16 v[130:133], v[150:153], v[200:203], v[130:133]
	v_mfma_f32_16x16x32_bf16 v[130:133], v[154:157], v[204:207], v[130:133]
	v_mfma_f32_16x16x32_bf16 v[114:117], v[150:153], v[208:211], v[114:117]
	v_mfma_f32_16x16x32_bf16 v[114:117], v[154:157], v[212:215], v[114:117]
	v_mfma_f32_16x16x32_bf16 v[110:113], v[158:161], v[208:211], v[110:113]
	v_mfma_f32_16x16x32_bf16 v[110:113], v[162:165], v[212:215], v[110:113]
	v_mfma_f32_16x16x32_bf16 v[106:109], v[174:177], v[208:211], v[106:109]
	v_mfma_f32_16x16x32_bf16 v[106:109], v[178:181], v[212:215], v[106:109]
	v_mfma_f32_16x16x32_bf16 v[102:105], v[182:185], v[208:211], v[102:105]
	v_mfma_f32_16x16x32_bf16 v[102:105], v[186:189], v[212:215], v[102:105]
	v_mfma_f32_16x16x32_bf16 v[86:89], v[182:185], v[220:223], v[86:89]
	v_mfma_f32_16x16x32_bf16 v[86:89], v[186:189], v[224:227], v[86:89]
	v_mfma_f32_16x16x32_bf16 v[90:93], v[174:177], v[220:223], v[90:93]
	v_mfma_f32_16x16x32_bf16 v[90:93], v[178:181], v[224:227], v[90:93]
	v_mfma_f32_16x16x32_bf16 v[94:97], v[158:161], v[220:223], v[94:97]
	v_mfma_f32_16x16x32_bf16 v[94:97], v[162:165], v[224:227], v[94:97]
	v_mfma_f32_16x16x32_bf16 v[98:101], v[150:153], v[220:223], v[98:101]
	v_mfma_f32_16x16x32_bf16 v[98:101], v[154:157], v[224:227], v[98:101]
	s_waitcnt vmcnt(8)
	s_barrier
	s_setprio 0
	ds_read_b128 v[190:193], v171 offset:49152
	ds_read_b128 v[196:199], v171 offset:50176
	ds_read_b128 v[200:203], v171 offset:51200
	ds_read_b128 v[204:207], v171 offset:52224
	ds_read_b128 v[208:211], v171 offset:53248
	ds_read_b128 v[212:215], v171 offset:54272
	ds_read_b128 v[220:223], v171 offset:55296
	ds_read_b128 v[224:227], v171 offset:56320
	s_add_u32 s0, s90, 0x80
	s_addc_u32 s1, s91, 0
	s_add_u32 vcc_lo, s0, 0x100000
	s_addc_u32 vcc_hi, s1, 0
	s_add_i32 m0, s27, 0x18000
	s_nop 0
	global_load_lds_dwordx4 v136, s[0:1]
	s_add_i32 m0, s27, 0x1a000
	s_nop 0
	global_load_lds_dwordx4 v140, s[0:1]
	s_add_i32 m0, s27, 0x1c000
	s_nop 0
	global_load_lds_dwordx4 v136, vcc
	s_add_i32 m0, s27, 0x1e000
	s_nop 0
	global_load_lds_dwordx4 v140, vcc
	s_waitcnt lgkmcnt(0)
	s_setprio 1
	v_mfma_f32_16x16x32_bf16 v[70:73], v[182:185], v[190:193], v[70:73]
	v_mfma_f32_16x16x32_bf16 v[70:73], v[186:189], v[196:199], v[70:73]
	v_mfma_f32_16x16x32_bf16 v[74:77], v[174:177], v[190:193], v[74:77]
	v_mfma_f32_16x16x32_bf16 v[74:77], v[178:181], v[196:199], v[74:77]
	v_mfma_f32_16x16x32_bf16 v[78:81], v[158:161], v[190:193], v[78:81]
	v_mfma_f32_16x16x32_bf16 v[78:81], v[162:165], v[196:199], v[78:81]
	v_mfma_f32_16x16x32_bf16 v[82:85], v[150:153], v[190:193], v[82:85]
	v_mfma_f32_16x16x32_bf16 v[82:85], v[154:157], v[196:199], v[82:85]
	v_mfma_f32_16x16x32_bf16 v[66:69], v[150:153], v[200:203], v[66:69]
	v_mfma_f32_16x16x32_bf16 v[66:69], v[154:157], v[204:207], v[66:69]
	v_mfma_f32_16x16x32_bf16 v[62:65], v[158:161], v[200:203], v[62:65]
	v_mfma_f32_16x16x32_bf16 v[62:65], v[162:165], v[204:207], v[62:65]
	v_mfma_f32_16x16x32_bf16 v[58:61], v[174:177], v[200:203], v[58:61]
	v_mfma_f32_16x16x32_bf16 v[58:61], v[178:181], v[204:207], v[58:61]
	v_mfma_f32_16x16x32_bf16 v[54:57], v[182:185], v[200:203], v[54:57]
	v_mfma_f32_16x16x32_bf16 v[54:57], v[186:189], v[204:207], v[54:57]
	v_mfma_f32_16x16x32_bf16 v[22:25], v[182:185], v[208:211], v[22:25]
	v_mfma_f32_16x16x32_bf16 v[22:25], v[186:189], v[212:215], v[22:25]
	v_mfma_f32_16x16x32_bf16 v[26:29], v[174:177], v[208:211], v[26:29]
	v_mfma_f32_16x16x32_bf16 v[26:29], v[178:181], v[212:215], v[26:29]
	v_mfma_f32_16x16x32_bf16 v[34:37], v[158:161], v[208:211], v[34:37]
	v_mfma_f32_16x16x32_bf16 v[34:37], v[162:165], v[212:215], v[34:37]
	v_mfma_f32_16x16x32_bf16 v[42:45], v[150:153], v[208:211], v[42:45]
	v_mfma_f32_16x16x32_bf16 v[42:45], v[154:157], v[212:215], v[42:45]
	v_mfma_f32_16x16x32_bf16 v[18:21], v[150:153], v[220:223], v[18:21]
	v_mfma_f32_16x16x32_bf16 v[18:21], v[154:157], v[224:227], v[18:21]
	v_mfma_f32_16x16x32_bf16 v[14:17], v[158:161], v[220:223], v[14:17]
	v_mfma_f32_16x16x32_bf16 v[14:17], v[162:165], v[224:227], v[14:17]
	v_mfma_f32_16x16x32_bf16 v[8:11], v[174:177], v[220:223], v[10:13]
	v_mfma_f32_16x16x32_bf16 v[10:13], v[178:181], v[224:227], v[8:11]
	v_mfma_f32_16x16x32_bf16 v[4:7], v[182:185], v[220:223], v[4:7]
	v_mfma_f32_16x16x32_bf16 v[6:9], v[186:189], v[224:227], v[4:7]
	s_waitcnt vmcnt(6)
	s_barrier
	s_setprio 0
	s_add_i32 s23, s23, 2
	s_add_u32 s88, s88, 0x100
	s_addc_u32 s89, s89, 0
	s_add_u32 s9, s9, 0x100
	s_addc_u32 s21, s21, 0
	s_cmp_gt_u32 s23, 61
	s_cbranch_scc0 .LBB0_349
	s_branch .Lip_exit
; #define PG8_STAGE(bufoff, gbase, voff) do { _Pragma("unroll") for (int _i = 0; _i < 2; ++_i) \
;         __builtin_amdgcn_global_load_lds((const unsigned*)((const char*)(gbase) + (voff)[_i]), (PG8_LAS unsigned*)(lds + (bufoff) + ldsw + _i * 8192), 16, 0, 0); } while (0)
; #define PG8_LDA(dst, b, h) do { _Pragma("unroll") for (int m = 0; m < 4; ++m) _Pragma("unroll") for (int k = 0; k < 2; ++k) dst[m][k] = *(const PG8_LAS bf16x8*)(lds + PG8_SA(b, h) + aoff + m * 2048 + k * 1024); } while (0)
; #define PG8_LDB(dst, b, h) do { _Pragma("unroll") for (int n = 0; n < 2; ++n) _Pragma("unroll") for (int k = 0; k < 2; ++k) dst[n][k] = *(const PG8_LAS bf16x8*)(lds + PG8_SB(b, h) + boff + n * 2048 + k * 1024); } while (0)
; #define PG8_MMA(ai, bj, At, Bt) do { __builtin_amdgcn_s_setprio(1); _Pragma("unroll") for (int m = 0; m < 4; ++m) _Pragma("unroll") for (int n = 0; n < 2; ++n) _Pragma("unroll") for (int k = 0; k < 2; ++k) \
;         acc[ai][bj][m][n] = __builtin_amdgcn_mfma_f32_16x16x32_bf16(Bt[n][k], At[m][k], acc[ai][bj][m][n], 0, 0, 0); __builtin_amdgcn_s_setprio(0); } while (0)
; #define PG8_BAR __builtin_amdgcn_s_barrier()
; template <class Epi, class Sched, bool ALIGN_EPI = false, bool SP2 = false>
; __device__ __forceinline__ void gemm_phase(PG8_LAS unsigned char* lds, const Gemm g, const Sched& S, const Epi& E) {
;     ...
;             const bool last = (t == nt - 2);
;             const char* a1 = cA + (size_t)(t + 1) * kstep;
;             const char* a2 = last ? nA : cA + (size_t)(t + 2) * kstep; const char* b2 = last ? nB : cB + (size_t)(t + 2) * kstep;
;             const char* a3 = a2 + kstep; const char* b3 = b2 + kstep;
;             if (last && has_next) S.a_ready(nxt);
;             if constexpr (Epi::MIDK) { if (t == (nt >> 1)) { E.midk(acc, wr, fr); asm volatile("s_waitcnt lgkmcnt(0)" ::: "memory"); } }
;             if constexpr (SP2) {
;             PG8_LDB(B0, 0, 0); PG8_LDB(B1, 0, 1); PG8_SCHED; PG8_LDA(At, 0, 0); PG8_STAGE(PG8_SA(1, 1), a1 + hstep, voffA);
;             PG8_WAIT_V(8); PG8_WAIT_L(0); PG8_BAR; PG8_MMA(0, 0, At, B0); PG8_MMA(0, 1, At, B1); PG8_BAR; PG8_SCHED;
;             PG8_LDA(At, 0, 1); PG8_STAGE(PG8_SB(0, 0), b2, voffB); PG8_STAGE(PG8_SB(0, 1), b2 + hstep, voffB); PG8_STAGE(PG8_SA(0, 0), a2, voffA);
;             PG8_WAIT_V(8); PG8_WAIT_L(0); PG8_BAR; PG8_MMA(1, 0, At, B0); PG8_MMA(1, 1, At, B1); PG8_BAR; PG8_SCHED;
.Lip_h1:
	ds_read_b128 v[150:153], v169
	ds_read_b128 v[154:157], v169 offset:1024
	ds_read_b128 v[158:161], v169 offset:2048
	ds_read_b128 v[162:165], v169 offset:3072
	ds_read_b128 v[174:177], v170
	ds_read_b128 v[178:181], v170 offset:1024
	ds_read_b128 v[182:185], v170 offset:2048
	ds_read_b128 v[186:189], v170 offset:3072
	s_add_u32 s0, s88, 0xfff00080
	s_addc_u32 s1, s89, -1
	s_cmp_eq_u32 s23, 60
	s_cselect_b32 s93, s51, s1
	s_cselect_b32 s92, s50, s0
	s_cselect_b32 s91, s53, s21
	s_cselect_b32 s90, s52, s9
	ds_read_b128 v[190:193], v171
	ds_read_b128 v[196:199], v171 offset:1024
	ds_read_b128 v[200:203], v171 offset:2048
	ds_read_b128 v[204:207], v171 offset:3072
	ds_read_b128 v[208:211], v171 offset:4096
	ds_read_b128 v[212:215], v171 offset:5120
	ds_read_b128 v[220:223], v171 offset:6144
	ds_read_b128 v[224:227], v171 offset:7168
	s_add_u32 s0, s88, 0xfff00000
	s_addc_u32 s1, s89, -1
	s_add_i32 m0, s27, 0x8000
	s_nop 0
	global_load_lds_dwordx4 v134, s[0:1]
	s_add_i32 m0, s27, 0xa000
	s_nop 0
	global_load_lds_dwordx4 v138, s[0:1]
	s_add_i32 m0, s27, 0xc000
	s_nop 0
	global_load_lds_dwordx4 v134, s[88:89]
	s_add_i32 m0, s27, 0xe000
	s_nop 0
	global_load_lds_dwordx4 v138, s[88:89]
	s_sleep 2
	s_waitcnt lgkmcnt(0)
	s_setprio 2
	s_waitcnt vmcnt(8)
	s_barrier
	v_mfma_f32_16x16x32_bf16 v[38:41], v[150:153], v[190:193], v[38:41]
	v_mfma_f32_16x16x32_bf16 v[38:41], v[154:157], v[196:199], v[38:41]
	v_mfma_f32_16x16x32_bf16 v[30:33], v[158:161], v[190:193], v[30:33]
	v_mfma_f32_16x16x32_bf16 v[30:33], v[162:165], v[196:199], v[30:33]
	v_mfma_f32_16x16x32_bf16 v[50:53], v[174:177], v[190:193], v[50:53]
	v_mfma_f32_16x16x32_bf16 v[50:53], v[178:181], v[196:199], v[50:53]
	v_mfma_f32_16x16x32_bf16 v[46:49], v[182:185], v[190:193], v[46:49]
	v_mfma_f32_16x16x32_bf16 v[46:49], v[186:189], v[196:199], v[46:49]
	v_mfma_f32_16x16x32_bf16 v[118:121], v[182:185], v[200:203], v[118:121]
	v_mfma_f32_16x16x32_bf16 v[118:121], v[186:189], v[204:207], v[118:121]
	v_mfma_f32_16x16x32_bf16 v[122:125], v[174:177], v[200:203], v[122:125]
	v_mfma_f32_16x16x32_bf16 v[122:125], v[178:181], v[204:207], v[122:125]
	v_mfma_f32_16x16x32_bf16 v[126:129], v[158:161], v[200:203], v[126:129]
	v_mfma_f32_16x16x32_bf16 v[126:129], v[162:165], v[204:207], v[126:129]
	v_mfma_f32_16x16x32_bf16 v[130:133], v[150:153], v[200:203], v[130:133]
	v_mfma_f32_16x16x32_bf16 v[130:133], v[154:157], v[204:207], v[130:133]
	v_mfma_f32_16x16x32_bf16 v[114:117], v[150:153], v[208:211], v[114:117]
	v_mfma_f32_16x16x32_bf16 v[114:117], v[154:157], v[212:215], v[114:117]
	v_mfma_f32_16x16x32_bf16 v[110:113], v[158:161], v[208:211], v[110:113]
	v_mfma_f32_16x16x32_bf16 v[110:113], v[162:165], v[212:215], v[110:113]
	v_mfma_f32_16x16x32_bf16 v[106:109], v[174:177], v[208:211], v[106:109]
	v_mfma_f32_16x16x32_bf16 v[106:109], v[178:181], v[212:215], v[106:109]
	v_mfma_f32_16x16x32_bf16 v[102:105], v[182:185], v[208:211], v[102:105]
	v_mfma_f32_16x16x32_bf16 v[102:105], v[186:189], v[212:215], v[102:105]
	v_mfma_f32_16x16x32_bf16 v[86:89], v[182:185], v[220:223], v[86:89]
	v_mfma_f32_16x16x32_bf16 v[86:89], v[186:189], v[224:227], v[86:89]
	v_mfma_f32_16x16x32_bf16 v[90:93], v[174:177], v[220:223], v[90:93]
	v_mfma_f32_16x16x32_bf16 v[90:93], v[178:181], v[224:227], v[90:93]
	v_mfma_f32_16x16x32_bf16 v[94:97], v[158:161], v[220:223], v[94:97]
	v_mfma_f32_16x16x32_bf16 v[94:97], v[162:165], v[224:227], v[94:97]
	v_mfma_f32_16x16x32_bf16 v[98:101], v[150:153], v[220:223], v[98:101]
	v_mfma_f32_16x16x32_bf16 v[98:101], v[154:157], v[224:227], v[98:101]
	s_setprio 0
	ds_read_b128 v[190:193], v171 offset:16384
	ds_read_b128 v[196:199], v171 offset:17408
	ds_read_b128 v[200:203], v171 offset:18432
	ds_read_b128 v[204:207], v171 offset:19456
	ds_read_b128 v[208:211], v171 offset:20480
	ds_read_b128 v[212:215], v171 offset:21504
	ds_read_b128 v[220:223], v171 offset:22528
	ds_read_b128 v[224:227], v171 offset:23552
	s_add_u32 vcc_lo, s90, 0x100000
	s_addc_u32 vcc_hi, s91, 0
	s_add_i32 m0, s27, 0x10000
	s_nop 0
	global_load_lds_dwordx4 v136, s[90:91]
	s_add_i32 m0, s27, 0x12000
	s_nop 0
	global_load_lds_dwordx4 v140, s[90:91]
	s_add_i32 m0, s27, 0x14000
	s_nop 0
	global_load_lds_dwordx4 v136, vcc
	s_add_i32 m0, s27, 0x16000
	s_nop 0
	global_load_lds_dwordx4 v140, vcc
	s_sleep 2
	s_waitcnt lgkmcnt(0)
	s_setprio 2
	s_waitcnt vmcnt(6)
	s_barrier
; #define PG8_STAGE(bufoff, gbase, voff) do { _Pragma("unroll") for (int _i = 0; _i < 2; ++_i) \
;         __builtin_amdgcn_global_load_lds((const unsigned*)((const char*)(gbase) + (voff)[_i]), (PG8_LAS unsigned*)(lds + (bufoff) + ldsw + _i * 8192), 16, 0, 0); } while (0)
; #define PG8_LDA(dst, b, h) do { _Pragma("unroll") for (int m = 0; m < 4; ++m) _Pragma("unroll") for (int k = 0; k < 2; ++k) dst[m][k] = *(const PG8_LAS bf16x8*)(lds + PG8_SA(b, h) + aoff + m * 2048 + k * 1024); } while (0)
; #define PG8_LDB(dst, b, h) do { _Pragma("unroll") for (int n = 0; n < 2; ++n) _Pragma("unroll") for (int k = 0; k < 2; ++k) dst[n][k] = *(const PG8_LAS bf16x8*)(lds + PG8_SB(b, h) + boff + n * 2048 + k * 1024); } while (0)
; #define PG8_MMA(ai, bj, At, Bt) do { __builtin_amdgcn_s_setprio(1); _Pragma("unroll") for (int m = 0; m < 4; ++m) _Pragma("unroll") for (int n = 0; n < 2; ++n) _Pragma("unroll") for (int k = 0; k < 2; ++k) \
;         acc[ai][bj][m][n] = __builtin_amdgcn_mfma_f32_16x16x32_bf16(Bt[n][k], At[m][k], acc[ai][bj][m][n], 0, 0, 0); __builtin_amdgcn_s_setprio(0); } while (0)
; #define PG8_WAIT_V(n) asm volatile("s_waitcnt vmcnt(" #n ")" ::: "memory")
; #define PG8_WAIT_L(n) asm volatile("s_waitcnt lgkmcnt(" #n ")" ::: "memory")
; #define PG8_BAR __builtin_amdgcn_s_barrier()
; #define PG8_SCHED __builtin_amdgcn_sched_barrier(0)
; template <class Epi, class Sched, bool ALIGN_EPI = false, bool SP2 = false>
; __device__ __forceinline__ void gemm_phase(PG8_LAS unsigned char* lds, const Gemm g, const Sched& S, const Epi& E) {
;     ...
;             PG8_WAIT_V(8); PG8_WAIT_L(0); PG8_BAR; PG8_MMA(1, 0, At, B0); PG8_MMA(1, 1, At, B1); PG8_BAR; PG8_SCHED;
;             PG8_LDB(B0, 1, 0); PG8_LDB(B1, 1, 1); PG8_SCHED; PG8_LDA(At, 1, 0); PG8_STAGE(PG8_SA(0, 1), a2 + hstep, voffA);
;             PG8_WAIT_V(8); PG8_WAIT_L(0); PG8_BAR; PG8_MMA(0, 0, At, B0); PG8_MMA(0, 1, At, B1); PG8_BAR; PG8_SCHED;
	v_mfma_f32_16x16x32_bf16 v[82:85], v[150:153], v[190:193], v[82:85]
	v_mfma_f32_16x16x32_bf16 v[82:85], v[154:157], v[196:199], v[82:85]
	v_mfma_f32_16x16x32_bf16 v[78:81], v[158:161], v[190:193], v[78:81]
	v_mfma_f32_16x16x32_bf16 v[78:81], v[162:165], v[196:199], v[78:81]
	v_mfma_f32_16x16x32_bf16 v[74:77], v[174:177], v[190:193], v[74:77]
	v_mfma_f32_16x16x32_bf16 v[74:77], v[178:181], v[196:199], v[74:77]
	v_mfma_f32_16x16x32_bf16 v[70:73], v[182:185], v[190:193], v[70:73]
	v_mfma_f32_16x16x32_bf16 v[70:73], v[186:189], v[196:199], v[70:73]
	v_mfma_f32_16x16x32_bf16 v[54:57], v[182:185], v[200:203], v[54:57]
	v_mfma_f32_16x16x32_bf16 v[54:57], v[186:189], v[204:207], v[54:57]
	v_mfma_f32_16x16x32_bf16 v[58:61], v[174:177], v[200:203], v[58:61]
	v_mfma_f32_16x16x32_bf16 v[58:61], v[178:181], v[204:207], v[58:61]
	v_mfma_f32_16x16x32_bf16 v[62:65], v[158:161], v[200:203], v[62:65]
	v_mfma_f32_16x16x32_bf16 v[62:65], v[162:165], v[204:207], v[62:65]
	v_mfma_f32_16x16x32_bf16 v[66:69], v[150:153], v[200:203], v[66:69]
	v_mfma_f32_16x16x32_bf16 v[66:69], v[154:157], v[204:207], v[66:69]
	v_mfma_f32_16x16x32_bf16 v[42:45], v[150:153], v[208:211], v[42:45]
	v_mfma_f32_16x16x32_bf16 v[42:45], v[154:157], v[212:215], v[42:45]
	v_mfma_f32_16x16x32_bf16 v[34:37], v[158:161], v[208:211], v[34:37]
	v_mfma_f32_16x16x32_bf16 v[34:37], v[162:165], v[212:215], v[34:37]
	v_mfma_f32_16x16x32_bf16 v[26:29], v[174:177], v[208:211], v[26:29]
	v_mfma_f32_16x16x32_bf16 v[26:29], v[178:181], v[212:215], v[26:29]
	v_mfma_f32_16x16x32_bf16 v[22:25], v[182:185], v[208:211], v[22:25]
	v_mfma_f32_16x16x32_bf16 v[22:25], v[186:189], v[212:215], v[22:25]
	v_mfma_f32_16x16x32_bf16 v[4:7], v[182:185], v[220:223], v[6:9]
	v_mfma_f32_16x16x32_bf16 v[4:7], v[186:189], v[224:227], v[4:7]
	v_mfma_f32_16x16x32_bf16 v[10:13], v[174:177], v[220:223], v[10:13]
	v_mfma_f32_16x16x32_bf16 v[10:13], v[178:181], v[224:227], v[10:13]
	v_mfma_f32_16x16x32_bf16 v[14:17], v[158:161], v[220:223], v[14:17]
	v_mfma_f32_16x16x32_bf16 v[14:17], v[162:165], v[224:227], v[14:17]
	v_mfma_f32_16x16x32_bf16 v[18:21], v[150:153], v[220:223], v[18:21]
	v_mfma_f32_16x16x32_bf16 v[18:21], v[154:157], v[224:227], v[18:21]
	s_setprio 0
	s_add_i32 s0, 0, 0x18000
	v_add_u32_e32 v3, s0, v167
	s_add_i32 s1, 0, 0x1c000
	ds_read_b128 v[150:153], v3
	ds_read_b128 v[154:157], v3 offset:1024
	ds_read_b128 v[158:161], v3 offset:2048
	ds_read_b128 v[162:165], v3 offset:3072
	v_add_u32_e32 v3, s1, v167
	ds_read_b128 v[174:177], v3
	ds_read_b128 v[178:181], v3 offset:1024
	ds_read_b128 v[182:185], v3 offset:2048
	ds_read_b128 v[186:189], v3 offset:3072
	ds_read_b128 v[190:193], v171 offset:32768
	ds_read_b128 v[196:199], v171 offset:33792
	ds_read_b128 v[200:203], v171 offset:34816
	ds_read_b128 v[204:207], v171 offset:35840
	ds_read_b128 v[208:211], v171 offset:36864
	ds_read_b128 v[212:215], v171 offset:37888
	ds_read_b128 v[220:223], v171 offset:38912
	ds_read_b128 v[224:227], v171 offset:39936
	s_add_u32 vcc_lo, s92, 0x100000
	s_addc_u32 vcc_hi, s93, 0
	s_mov_b32 m0, s27
	s_nop 0
	global_load_lds_dwordx4 v134, s[92:93]
	s_add_i32 m0, s27, 0x2000
	s_nop 0
	global_load_lds_dwordx4 v138, s[92:93]
	s_add_i32 m0, s27, 0x4000
	s_nop 0
	global_load_lds_dwordx4 v134, vcc
	s_add_i32 m0, s27, 0x6000
	s_nop 0
	global_load_lds_dwordx4 v138, vcc
	s_sleep 2
	s_waitcnt lgkmcnt(0)
	s_setprio 2
	s_waitcnt vmcnt(8)
	s_barrier
; #define PG8_STAGE(bufoff, gbase, voff) do { _Pragma("unroll") for (int _i = 0; _i < 2; ++_i) \
;         __builtin_amdgcn_global_load_lds((const unsigned*)((const char*)(gbase) + (voff)[_i]), (PG8_LAS unsigned*)(lds + (bufoff) + ldsw + _i * 8192), 16, 0, 0); } while (0)
; #define PG8_LDA(dst, b, h) do { _Pragma("unroll") for (int m = 0; m < 4; ++m) _Pragma("unroll") for (int k = 0; k < 2; ++k) dst[m][k] = *(const PG8_LAS bf16x8*)(lds + PG8_SA(b, h) + aoff + m * 2048 + k * 1024); } while (0)
; #define PG8_WAIT_V(n) asm volatile("s_waitcnt vmcnt(" #n ")" ::: "memory")
; template <class Epi, class Sched, bool ALIGN_EPI = false, bool SP2 = false>
; __device__ __forceinline__ void gemm_phase(PG8_LAS unsigned char* lds, const Gemm g, const Sched& S, const Epi& E) {
;     ...
;         for (int t = 0; t < nt; t += 2) {
;             const bool last = (t == nt - 2);
;             const char* a1 = cA + (size_t)(t + 1) * kstep;
;             const char* a2 = last ? nA : cA + (size_t)(t + 2) * kstep; const char* b2 = last ? nB : cB + (size_t)(t + 2) * kstep;
;             const char* a3 = a2 + kstep; const char* b3 = b2 + kstep;
;             if (last && has_next) S.a_ready(nxt);
;             if constexpr (Epi::MIDK) { if (t == (nt >> 1)) { E.midk(acc, wr, fr); asm volatile("s_waitcnt lgkmcnt(0)" ::: "memory"); } }
;             if constexpr (SP2) {
;             PG8_LDB(B0, 0, 0); PG8_LDB(B1, 0, 1); PG8_SCHED; PG8_LDA(At, 0, 0); PG8_STAGE(PG8_SA(1, 1), a1 + hstep, voffA);
;             PG8_WAIT_V(8); PG8_WAIT_L(0); PG8_BAR; PG8_MMA(0, 0, At, B0); PG8_MMA(0, 1, At, B1); PG8_BAR; PG8_SCHED;
;             PG8_LDA(At, 0, 1); PG8_STAGE(PG8_SB(0, 0), b2, voffB); PG8_STAGE(PG8_SB(0, 1), b2 + hstep, voffB); PG8_STAGE(PG8_SA(0, 0), a2, voffA);
;             PG8_WAIT_V(8); PG8_WAIT_L(0); PG8_BAR; PG8_MMA(1, 0, At, B0); PG8_MMA(1, 1, At, B1); PG8_BAR; PG8_SCHED;
;             PG8_LDB(B0, 1, 0); PG8_LDB(B1, 1, 1); PG8_SCHED; PG8_LDA(At, 1, 0); PG8_STAGE(PG8_SA(0, 1), a2 + hstep, voffA);
;             PG8_WAIT_V(8); PG8_WAIT_L(0); PG8_BAR; PG8_MMA(0, 0, At, B0); PG8_MMA(0, 1, At, B1); PG8_BAR; PG8_SCHED;
;             PG8_LDA(At, 1, 1); PG8_STAGE(PG8_SB(1, 0), b3, voffB); PG8_STAGE(PG8_SB(1, 1), b3 + hstep, voffB); PG8_STAGE(PG8_SA(1, 0), a3, voffA);
;             PG8_WAIT_V(8); PG8_WAIT_L(0); PG8_BAR; PG8_MMA(1, 0, At, B0); PG8_MMA(1, 1, At, B1); PG8_BAR; PG8_SCHED;
	v_mfma_f32_16x16x32_bf16 v[38:41], v[150:153], v[190:193], v[38:41]
	v_mfma_f32_16x16x32_bf16 v[38:41], v[154:157], v[196:199], v[38:41]
	v_mfma_f32_16x16x32_bf16 v[30:33], v[158:161], v[190:193], v[30:33]
	v_mfma_f32_16x16x32_bf16 v[30:33], v[162:165], v[196:199], v[30:33]
	v_mfma_f32_16x16x32_bf16 v[50:53], v[174:177], v[190:193], v[50:53]
	v_mfma_f32_16x16x32_bf16 v[50:53], v[178:181], v[196:199], v[50:53]
	v_mfma_f32_16x16x32_bf16 v[46:49], v[182:185], v[190:193], v[46:49]
	v_mfma_f32_16x16x32_bf16 v[46:49], v[186:189], v[196:199], v[46:49]
	v_mfma_f32_16x16x32_bf16 v[118:121], v[182:185], v[200:203], v[118:121]
	v_mfma_f32_16x16x32_bf16 v[118:121], v[186:189], v[204:207], v[118:121]
	v_mfma_f32_16x16x32_bf16 v[122:125], v[174:177], v[200:203], v[122:125]
	v_mfma_f32_16x16x32_bf16 v[122:125], v[178:181], v[204:207], v[122:125]
	v_mfma_f32_16x16x32_bf16 v[126:129], v[158:161], v[200:203], v[126:129]
	v_mfma_f32_16x16x32_bf16 v[126:129], v[162:165], v[204:207], v[126:129]
	v_mfma_f32_16x16x32_bf16 v[130:133], v[150:153], v[200:203], v[130:133]
	v_mfma_f32_16x16x32_bf16 v[130:133], v[154:157], v[204:207], v[130:133]
	v_mfma_f32_16x16x32_bf16 v[114:117], v[150:153], v[208:211], v[114:117]
	v_mfma_f32_16x16x32_bf16 v[114:117], v[154:157], v[212:215], v[114:117]
	v_mfma_f32_16x16x32_bf16 v[110:113], v[158:161], v[208:211], v[110:113]
	v_mfma_f32_16x16x32_bf16 v[110:113], v[162:165], v[212:215], v[110:113]
	v_mfma_f32_16x16x32_bf16 v[106:109], v[174:177], v[208:211], v[106:109]
	v_mfma_f32_16x16x32_bf16 v[106:109], v[178:181], v[212:215], v[106:109]
	v_mfma_f32_16x16x32_bf16 v[102:105], v[182:185], v[208:211], v[102:105]
	v_mfma_f32_16x16x32_bf16 v[102:105], v[186:189], v[212:215], v[102:105]
	v_mfma_f32_16x16x32_bf16 v[86:89], v[182:185], v[220:223], v[86:89]
	v_mfma_f32_16x16x32_bf16 v[86:89], v[186:189], v[224:227], v[86:89]
	v_mfma_f32_16x16x32_bf16 v[90:93], v[174:177], v[220:223], v[90:93]
	v_mfma_f32_16x16x32_bf16 v[90:93], v[178:181], v[224:227], v[90:93]
	v_mfma_f32_16x16x32_bf16 v[94:97], v[158:161], v[220:223], v[94:97]
	v_mfma_f32_16x16x32_bf16 v[94:97], v[162:165], v[224:227], v[94:97]
	v_mfma_f32_16x16x32_bf16 v[98:101], v[150:153], v[220:223], v[98:101]
	v_mfma_f32_16x16x32_bf16 v[98:101], v[154:157], v[224:227], v[98:101]
	s_setprio 0
	ds_read_b128 v[190:193], v171 offset:49152
	ds_read_b128 v[196:199], v171 offset:50176
	ds_read_b128 v[200:203], v171 offset:51200
	ds_read_b128 v[204:207], v171 offset:52224
	ds_read_b128 v[208:211], v171 offset:53248
	ds_read_b128 v[212:215], v171 offset:54272
	ds_read_b128 v[220:223], v171 offset:55296
	ds_read_b128 v[224:227], v171 offset:56320
	s_add_u32 s0, s90, 0x80
	s_addc_u32 s1, s91, 0
	s_add_u32 vcc_lo, s0, 0x100000
	s_addc_u32 vcc_hi, s1, 0
	s_add_i32 m0, s27, 0x18000
	s_nop 0
	global_load_lds_dwordx4 v136, s[0:1]
	s_add_i32 m0, s27, 0x1a000
	s_nop 0
	global_load_lds_dwordx4 v140, s[0:1]
	s_add_i32 m0, s27, 0x1c000
	s_nop 0
	global_load_lds_dwordx4 v136, vcc
	s_add_i32 m0, s27, 0x1e000
	s_nop 0
	global_load_lds_dwordx4 v140, vcc
	s_sleep 2
	s_waitcnt lgkmcnt(0)
	s_setprio 2
	s_waitcnt vmcnt(6)
	s_barrier
	v_mfma_f32_16x16x32_bf16 v[70:73], v[182:185], v[190:193], v[70:73]
	v_mfma_f32_16x16x32_bf16 v[70:73], v[186:189], v[196:199], v[70:73]
	v_mfma_f32_16x16x32_bf16 v[74:77], v[174:177], v[190:193], v[74:77]
	v_mfma_f32_16x16x32_bf16 v[74:77], v[178:181], v[196:199], v[74:77]
	v_mfma_f32_16x16x32_bf16 v[78:81], v[158:161], v[190:193], v[78:81]
	v_mfma_f32_16x16x32_bf16 v[78:81], v[162:165], v[196:199], v[78:81]
	v_mfma_f32_16x16x32_bf16 v[82:85], v[150:153], v[190:193], v[82:85]
	v_mfma_f32_16x16x32_bf16 v[82:85], v[154:157], v[196:199], v[82:85]
	v_mfma_f32_16x16x32_bf16 v[66:69], v[150:153], v[200:203], v[66:69]
	v_mfma_f32_16x16x32_bf16 v[66:69], v[154:157], v[204:207], v[66:69]
	v_mfma_f32_16x16x32_bf16 v[62:65], v[158:161], v[200:203], v[62:65]
	v_mfma_f32_16x16x32_bf16 v[62:65], v[162:165], v[204:207], v[62:65]
	v_mfma_f32_16x16x32_bf16 v[58:61], v[174:177], v[200:203], v[58:61]
	v_mfma_f32_16x16x32_bf16 v[58:61], v[178:181], v[204:207], v[58:61]
	v_mfma_f32_16x16x32_bf16 v[54:57], v[182:185], v[200:203], v[54:57]
	v_mfma_f32_16x16x32_bf16 v[54:57], v[186:189], v[204:207], v[54:57]
	v_mfma_f32_16x16x32_bf16 v[22:25], v[182:185], v[208:211], v[22:25]
	v_mfma_f32_16x16x32_bf16 v[22:25], v[186:189], v[212:215], v[22:25]
	v_mfma_f32_16x16x32_bf16 v[26:29], v[174:177], v[208:211], v[26:29]
	v_mfma_f32_16x16x32_bf16 v[26:29], v[178:181], v[212:215], v[26:29]
	v_mfma_f32_16x16x32_bf16 v[34:37], v[158:161], v[208:211], v[34:37]
	v_mfma_f32_16x16x32_bf16 v[34:37], v[162:165], v[212:215], v[34:37]
	v_mfma_f32_16x16x32_bf16 v[42:45], v[150:153], v[208:211], v[42:45]
	v_mfma_f32_16x16x32_bf16 v[42:45], v[154:157], v[212:215], v[42:45]
	v_mfma_f32_16x16x32_bf16 v[18:21], v[150:153], v[220:223], v[18:21]
	v_mfma_f32_16x16x32_bf16 v[18:21], v[154:157], v[224:227], v[18:21]
	v_mfma_f32_16x16x32_bf16 v[14:17], v[158:161], v[220:223], v[14:17]
	v_mfma_f32_16x16x32_bf16 v[14:17], v[162:165], v[224:227], v[14:17]
	v_mfma_f32_16x16x32_bf16 v[8:11], v[174:177], v[220:223], v[10:13]
	v_mfma_f32_16x16x32_bf16 v[10:13], v[178:181], v[224:227], v[8:11]
	v_mfma_f32_16x16x32_bf16 v[4:7], v[182:185], v[220:223], v[4:7]
	v_mfma_f32_16x16x32_bf16 v[6:9], v[186:189], v[224:227], v[4:7]
	s_setprio 0
	s_add_i32 s23, s23, 2
	s_add_u32 s88, s88, 0x100
	s_addc_u32 s89, s89, 0
	s_add_u32 s9, s9, 0x100
	s_addc_u32 s21, s21, 0
	s_cmp_gt_u32 s23, 61
	s_cbranch_scc0 .Lip_h1

; #define PG8_STAGE(bufoff, gbase, voff) do { _Pragma("unroll") for (int _i = 0; _i < 2; ++_i) \
;         __builtin_amdgcn_global_load_lds((const unsigned*)((const char*)(gbase) + (voff)[_i]), (PG8_LAS unsigned*)(lds + (bufoff) + ldsw + _i * 8192), 16, 0, 0); } while (0)
; #define PG8_LDA(dst, b, h) do { _Pragma("unroll") for (int m = 0; m < 4; ++m) _Pragma("unroll") for (int k = 0; k < 2; ++k) dst[m][k] = *(const PG8_LAS bf16x8*)(lds + PG8_SA(b, h) + aoff + m * 2048 + k * 1024); } while (0)
; #define PG8_LDB(dst, b, h) do { _Pragma("unroll") for (int n = 0; n < 2; ++n) _Pragma("unroll") for (int k = 0; k < 2; ++k) dst[n][k] = *(const PG8_LAS bf16x8*)(lds + PG8_SB(b, h) + boff + n * 2048 + k * 1024); } while (0)
; #define PG8_MMA(ai, bj, At, Bt) do { __builtin_amdgcn_s_setprio(1); _Pragma("unroll") for (int m = 0; m < 4; ++m) _Pragma("unroll") for (int n = 0; n < 2; ++n) _Pragma("unroll") for (int k = 0; k < 2; ++k) \
;         acc[ai][bj][m][n] = __builtin_amdgcn_mfma_f32_16x16x32_bf16(Bt[n][k], At[m][k], acc[ai][bj][m][n], 0, 0, 0); __builtin_amdgcn_s_setprio(0); } while (0)
; #define PG8_BAR __builtin_amdgcn_s_barrier()
; template <class Epi, class Sched, bool ALIGN_EPI = false, bool SP2 = false>
; __device__ __forceinline__ void gemm_phase(PG8_LAS unsigned char* lds, const Gemm g, const Sched& S, const Epi& E) {
;     ...
;             const bool last = (t == nt - 2);
;             const char* a1 = cA + (size_t)(t + 1) * kstep;
;             const char* a2 = last ? nA : cA + (size_t)(t + 2) * kstep; const char* b2 = last ? nB : cB + (size_t)(t + 2) * kstep;
;             const char* a3 = a2 + kstep; const char* b3 = b2 + kstep;
;             if (last && has_next) S.a_ready(nxt);
;             if constexpr (Epi::MIDK) { if (t == (nt >> 1)) { E.midk(acc, wr, fr); asm volatile("s_waitcnt lgkmcnt(0)" ::: "memory"); } }
;             if constexpr (SP2) {
;             PG8_LDB(B0, 0, 0); PG8_LDB(B1, 0, 1); PG8_SCHED; PG8_LDA(At, 0, 0); PG8_STAGE(PG8_SA(1, 1), a1 + hstep, voffA);
;             PG8_WAIT_V(8); PG8_WAIT_L(0); PG8_BAR; PG8_MMA(0, 0, At, B0); PG8_MMA(0, 1, At, B1); PG8_BAR; PG8_SCHED;
;             PG8_LDA(At, 0, 1); PG8_STAGE(PG8_SB(0, 0), b2, voffB); PG8_STAGE(PG8_SB(0, 1), b2 + hstep, voffB); PG8_STAGE(PG8_SA(0, 0), a2, voffA);
;             PG8_WAIT_V(8); PG8_WAIT_L(0); PG8_BAR; PG8_MMA(1, 0, At, B0); PG8_MMA(1, 1, At, B1); PG8_BAR; PG8_SCHED;
.LBB0_1251:
	ds_read_b128 v[130:133], v177
	ds_read_b128 v[134:137], v177 offset:1024
	ds_read_b128 v[138:141], v177 offset:2048
	ds_read_b128 v[142:145], v177 offset:3072
	ds_read_b128 v[162:165], v178
	ds_read_b128 v[180:183], v178 offset:1024
	ds_read_b128 v[184:187], v178 offset:2048
	ds_read_b128 v[188:191], v178 offset:3072
	s_add_u32 s40, s36, 0xfff00080
	s_addc_u32 s41, s37, -1
	s_cmp_eq_u32 s58, 60
	s_cselect_b32 s43, s15, s41
	s_cselect_b32 s42, s17, s40
	s_cselect_b32 s41, s54, s57
	s_cselect_b32 s40, s55, s56
	ds_read_b128 v[196:199], v179
	ds_read_b128 v[200:203], v179 offset:1024
	ds_read_b128 v[204:207], v179 offset:2048
	ds_read_b128 v[208:211], v179 offset:3072
	ds_read_b128 v[212:215], v179 offset:4096
	ds_read_b128 v[220:223], v179 offset:5120
	ds_read_b128 v[224:227], v179 offset:6144
	ds_read_b128 v[228:231], v179 offset:7168
	s_add_i32 m0, s24, 0xc000
	s_nop 0
	global_load_lds_dwordx4 v146, s[36:37]
	s_add_i32 m0, s24, 0xe000
	s_nop 0
	global_load_lds_dwordx4 v150, s[36:37]
	s_waitcnt lgkmcnt(0)
	s_setprio 1
	v_mfma_f32_16x16x32_bf16 v[126:129], v[130:133], v[196:199], v[126:129]
	v_mfma_f32_16x16x32_bf16 v[126:129], v[134:137], v[200:203], v[126:129]
	v_mfma_f32_16x16x32_bf16 v[122:125], v[138:141], v[196:199], v[122:125]
	v_mfma_f32_16x16x32_bf16 v[122:125], v[142:145], v[200:203], v[122:125]
	v_mfma_f32_16x16x32_bf16 v[118:121], v[162:165], v[196:199], v[118:121]
	v_mfma_f32_16x16x32_bf16 v[118:121], v[180:183], v[200:203], v[118:121]
	v_mfma_f32_16x16x32_bf16 v[114:117], v[184:187], v[196:199], v[114:117]
	v_mfma_f32_16x16x32_bf16 v[114:117], v[188:191], v[200:203], v[114:117]
	v_mfma_f32_16x16x32_bf16 v[98:101], v[184:187], v[204:207], v[98:101]
	v_mfma_f32_16x16x32_bf16 v[98:101], v[188:191], v[208:211], v[98:101]
	v_mfma_f32_16x16x32_bf16 v[102:105], v[162:165], v[204:207], v[102:105]
	v_mfma_f32_16x16x32_bf16 v[102:105], v[180:183], v[208:211], v[102:105]
	v_mfma_f32_16x16x32_bf16 v[106:109], v[138:141], v[204:207], v[106:109]
	v_mfma_f32_16x16x32_bf16 v[106:109], v[142:145], v[208:211], v[106:109]
	v_mfma_f32_16x16x32_bf16 v[110:113], v[130:133], v[204:207], v[110:113]
	v_mfma_f32_16x16x32_bf16 v[110:113], v[134:137], v[208:211], v[110:113]
	v_mfma_f32_16x16x32_bf16 v[94:97], v[130:133], v[212:215], v[94:97]
	v_mfma_f32_16x16x32_bf16 v[94:97], v[134:137], v[220:223], v[94:97]
	v_mfma_f32_16x16x32_bf16 v[90:93], v[138:141], v[212:215], v[90:93]
	v_mfma_f32_16x16x32_bf16 v[90:93], v[142:145], v[220:223], v[90:93]
	v_mfma_f32_16x16x32_bf16 v[86:89], v[162:165], v[212:215], v[86:89]
	v_mfma_f32_16x16x32_bf16 v[86:89], v[180:183], v[220:223], v[86:89]
	v_mfma_f32_16x16x32_bf16 v[82:85], v[184:187], v[212:215], v[82:85]
	v_mfma_f32_16x16x32_bf16 v[82:85], v[188:191], v[220:223], v[82:85]
	v_mfma_f32_16x16x32_bf16 v[66:69], v[184:187], v[224:227], v[66:69]
	v_mfma_f32_16x16x32_bf16 v[66:69], v[188:191], v[228:231], v[66:69]
	v_mfma_f32_16x16x32_bf16 v[70:73], v[162:165], v[224:227], v[70:73]
	v_mfma_f32_16x16x32_bf16 v[70:73], v[180:183], v[228:231], v[70:73]
	v_mfma_f32_16x16x32_bf16 v[74:77], v[138:141], v[224:227], v[74:77]
	v_mfma_f32_16x16x32_bf16 v[74:77], v[142:145], v[228:231], v[74:77]
	v_mfma_f32_16x16x32_bf16 v[78:81], v[130:133], v[224:227], v[78:81]
	v_mfma_f32_16x16x32_bf16 v[78:81], v[134:137], v[228:231], v[78:81]
	s_waitcnt vmcnt(8)
	s_barrier
	s_setprio 0
	ds_read_b128 v[196:199], v179 offset:16384
	ds_read_b128 v[200:203], v179 offset:17408
	ds_read_b128 v[204:207], v179 offset:18432
	ds_read_b128 v[208:211], v179 offset:19456
	ds_read_b128 v[212:215], v179 offset:20480
	ds_read_b128 v[220:223], v179 offset:21504
	ds_read_b128 v[224:227], v179 offset:22528
	ds_read_b128 v[228:231], v179 offset:23552
	s_add_u32 vcc_lo, s40, 0x100000
	s_addc_u32 vcc_hi, s41, 0
	s_add_i32 m0, s24, 0x10000
	s_nop 0
	global_load_lds_dwordx4 v148, s[40:41]
	s_add_i32 m0, s24, 0x12000
	s_nop 0
	global_load_lds_dwordx4 v152, s[40:41]
	s_add_i32 m0, s24, 0x14000
	s_nop 0
	global_load_lds_dwordx4 v148, vcc
	s_add_i32 m0, s24, 0x16000
	s_nop 0
	global_load_lds_dwordx4 v152, vcc
	s_mov_b32 m0, s24
	s_nop 0
	global_load_lds_dwordx4 v146, s[42:43]
	s_add_i32 m0, s24, 0x2000
	s_nop 0
	global_load_lds_dwordx4 v150, s[42:43]
	s_waitcnt lgkmcnt(0)
	s_setprio 1
	v_mfma_f32_16x16x32_bf16 v[62:65], v[130:133], v[196:199], v[62:65]
	v_mfma_f32_16x16x32_bf16 v[62:65], v[134:137], v[200:203], v[62:65]
	v_mfma_f32_16x16x32_bf16 v[58:61], v[138:141], v[196:199], v[58:61]
	v_mfma_f32_16x16x32_bf16 v[58:61], v[142:145], v[200:203], v[58:61]
	v_mfma_f32_16x16x32_bf16 v[54:57], v[162:165], v[196:199], v[54:57]
	v_mfma_f32_16x16x32_bf16 v[54:57], v[180:183], v[200:203], v[54:57]
	v_mfma_f32_16x16x32_bf16 v[50:53], v[184:187], v[196:199], v[50:53]
	v_mfma_f32_16x16x32_bf16 v[50:53], v[188:191], v[200:203], v[50:53]
	v_mfma_f32_16x16x32_bf16 v[34:37], v[184:187], v[204:207], v[34:37]
	v_mfma_f32_16x16x32_bf16 v[34:37], v[188:191], v[208:211], v[34:37]
	v_mfma_f32_16x16x32_bf16 v[38:41], v[162:165], v[204:207], v[38:41]
	v_mfma_f32_16x16x32_bf16 v[38:41], v[180:183], v[208:211], v[38:41]
	v_mfma_f32_16x16x32_bf16 v[42:45], v[138:141], v[204:207], v[42:45]
	v_mfma_f32_16x16x32_bf16 v[42:45], v[142:145], v[208:211], v[42:45]
	v_mfma_f32_16x16x32_bf16 v[46:49], v[130:133], v[204:207], v[46:49]
	v_mfma_f32_16x16x32_bf16 v[46:49], v[134:137], v[208:211], v[46:49]
	v_mfma_f32_16x16x32_bf16 v[30:33], v[130:133], v[212:215], v[30:33]
	v_mfma_f32_16x16x32_bf16 v[30:33], v[134:137], v[220:223], v[30:33]
	v_mfma_f32_16x16x32_bf16 v[26:29], v[138:141], v[212:215], v[26:29]
	v_mfma_f32_16x16x32_bf16 v[26:29], v[142:145], v[220:223], v[26:29]
	v_mfma_f32_16x16x32_bf16 v[22:25], v[162:165], v[212:215], v[22:25]
	v_mfma_f32_16x16x32_bf16 v[22:25], v[180:183], v[220:223], v[22:25]
	v_mfma_f32_16x16x32_bf16 v[18:21], v[184:187], v[212:215], v[18:21]
	v_mfma_f32_16x16x32_bf16 v[18:21], v[188:191], v[220:223], v[18:21]
	v_mfma_f32_16x16x32_bf16 v[2:5], v[184:187], v[224:227], v[2:5]
	v_mfma_f32_16x16x32_bf16 v[2:5], v[188:191], v[228:231], v[2:5]
	v_mfma_f32_16x16x32_bf16 v[6:9], v[162:165], v[224:227], v[6:9]
	v_mfma_f32_16x16x32_bf16 v[6:9], v[180:183], v[228:231], v[6:9]
	v_mfma_f32_16x16x32_bf16 v[10:13], v[138:141], v[224:227], v[10:13]
	v_mfma_f32_16x16x32_bf16 v[10:13], v[142:145], v[228:231], v[10:13]
	v_mfma_f32_16x16x32_bf16 v[14:17], v[130:133], v[224:227], v[14:17]
	v_mfma_f32_16x16x32_bf16 v[14:17], v[134:137], v[228:231], v[14:17]
	s_waitcnt vmcnt(8)
	s_barrier
; #define PG8_STAGE(bufoff, gbase, voff) do { _Pragma("unroll") for (int _i = 0; _i < 2; ++_i) \
;         __builtin_amdgcn_global_load_lds((const unsigned*)((const char*)(gbase) + (voff)[_i]), (PG8_LAS unsigned*)(lds + (bufoff) + ldsw + _i * 8192), 16, 0, 0); } while (0)
; #define PG8_LDA(dst, b, h) do { _Pragma("unroll") for (int m = 0; m < 4; ++m) _Pragma("unroll") for (int k = 0; k < 2; ++k) dst[m][k] = *(const PG8_LAS bf16x8*)(lds + PG8_SA(b, h) + aoff + m * 2048 + k * 1024); } while (0)
; #define PG8_WAIT_V(n) asm volatile("s_waitcnt vmcnt(" #n ")" ::: "memory")
; template <class Epi, class Sched, bool ALIGN_EPI = false, bool SP2 = false>
; __device__ __forceinline__ void gemm_phase(PG8_LAS unsigned char* lds, const Gemm g, const Sched& S, const Epi& E) {
;     ...
;         for (int t = 0; t < nt; t += 2) {
;             const bool last = (t == nt - 2);
;             const char* a1 = cA + (size_t)(t + 1) * kstep;
;             const char* a2 = last ? nA : cA + (size_t)(t + 2) * kstep; const char* b2 = last ? nB : cB + (size_t)(t + 2) * kstep;
;             const char* a3 = a2 + kstep; const char* b3 = b2 + kstep;
;             if (last && has_next) S.a_ready(nxt);
;             if constexpr (Epi::MIDK) { if (t == (nt >> 1)) { E.midk(acc, wr, fr); asm volatile("s_waitcnt lgkmcnt(0)" ::: "memory"); } }
;             if constexpr (SP2) {
;             PG8_LDB(B0, 0, 0); PG8_LDB(B1, 0, 1); PG8_SCHED; PG8_LDA(At, 0, 0); PG8_STAGE(PG8_SA(1, 1), a1 + hstep, voffA);
;             PG8_WAIT_V(8); PG8_WAIT_L(0); PG8_BAR; PG8_MMA(0, 0, At, B0); PG8_MMA(0, 1, At, B1); PG8_BAR; PG8_SCHED;
;             PG8_LDA(At, 0, 1); PG8_STAGE(PG8_SB(0, 0), b2, voffB); PG8_STAGE(PG8_SB(0, 1), b2 + hstep, voffB); PG8_STAGE(PG8_SA(0, 0), a2, voffA);
;             PG8_WAIT_V(8); PG8_WAIT_L(0); PG8_BAR; PG8_MMA(1, 0, At, B0); PG8_MMA(1, 1, At, B1); PG8_BAR; PG8_SCHED;
;             PG8_LDB(B0, 1, 0); PG8_LDB(B1, 1, 1); PG8_SCHED; PG8_LDA(At, 1, 0); PG8_STAGE(PG8_SA(0, 1), a2 + hstep, voffA);
;             PG8_WAIT_V(8); PG8_WAIT_L(0); PG8_BAR; PG8_MMA(0, 0, At, B0); PG8_MMA(0, 1, At, B1); PG8_BAR; PG8_SCHED;
;             PG8_LDA(At, 1, 1); PG8_STAGE(PG8_SB(1, 0), b3, voffB); PG8_STAGE(PG8_SB(1, 1), b3 + hstep, voffB); PG8_STAGE(PG8_SA(1, 0), a3, voffA);
;             PG8_WAIT_V(8); PG8_WAIT_L(0); PG8_BAR; PG8_MMA(1, 0, At, B0); PG8_MMA(1, 1, At, B1); PG8_BAR; PG8_SCHED;
	s_setprio 0
	s_add_i32 s59, 0, 0x18000
	s_add_i32 s60, 0, 0x1c000
	v_add_u32_e32 v142, s59, v166
	v_add_u32_e32 v188, s60, v166
	ds_read_b128 v[130:133], v142
	ds_read_b128 v[134:137], v142 offset:1024
	ds_read_b128 v[138:141], v142 offset:2048
	ds_read_b128 v[142:145], v142 offset:3072
	ds_read_b128 v[162:165], v188
	ds_read_b128 v[180:183], v188 offset:1024
	ds_read_b128 v[184:187], v188 offset:2048
	ds_read_b128 v[188:191], v188 offset:3072
	ds_read_b128 v[196:199], v179 offset:32768
	ds_read_b128 v[200:203], v179 offset:33792
	ds_read_b128 v[204:207], v179 offset:34816
	ds_read_b128 v[208:211], v179 offset:35840
	ds_read_b128 v[212:215], v179 offset:36864
	ds_read_b128 v[220:223], v179 offset:37888
	ds_read_b128 v[224:227], v179 offset:38912
	ds_read_b128 v[228:231], v179 offset:39936
	s_add_u32 vcc_lo, s42, 0x100000
	s_addc_u32 vcc_hi, s43, 0
	s_add_i32 m0, s24, 0x4000
	s_nop 0
	global_load_lds_dwordx4 v146, vcc
	s_add_i32 m0, s24, 0x6000
	s_nop 0
	global_load_lds_dwordx4 v150, vcc
	s_waitcnt lgkmcnt(0)
	s_setprio 1
	v_mfma_f32_16x16x32_bf16 v[126:129], v[130:133], v[196:199], v[126:129]
	v_mfma_f32_16x16x32_bf16 v[126:129], v[134:137], v[200:203], v[126:129]
	v_mfma_f32_16x16x32_bf16 v[122:125], v[138:141], v[196:199], v[122:125]
	v_mfma_f32_16x16x32_bf16 v[122:125], v[142:145], v[200:203], v[122:125]
	v_mfma_f32_16x16x32_bf16 v[118:121], v[162:165], v[196:199], v[118:121]
	v_mfma_f32_16x16x32_bf16 v[118:121], v[180:183], v[200:203], v[118:121]
	v_mfma_f32_16x16x32_bf16 v[114:117], v[184:187], v[196:199], v[114:117]
	v_mfma_f32_16x16x32_bf16 v[114:117], v[188:191], v[200:203], v[114:117]
	v_mfma_f32_16x16x32_bf16 v[98:101], v[184:187], v[204:207], v[98:101]
	v_mfma_f32_16x16x32_bf16 v[98:101], v[188:191], v[208:211], v[98:101]
	v_mfma_f32_16x16x32_bf16 v[102:105], v[162:165], v[204:207], v[102:105]
	v_mfma_f32_16x16x32_bf16 v[102:105], v[180:183], v[208:211], v[102:105]
	v_mfma_f32_16x16x32_bf16 v[106:109], v[138:141], v[204:207], v[106:109]
	v_mfma_f32_16x16x32_bf16 v[106:109], v[142:145], v[208:211], v[106:109]
	v_mfma_f32_16x16x32_bf16 v[110:113], v[130:133], v[204:207], v[110:113]
	v_mfma_f32_16x16x32_bf16 v[110:113], v[134:137], v[208:211], v[110:113]
	v_mfma_f32_16x16x32_bf16 v[94:97], v[130:133], v[212:215], v[94:97]
	v_mfma_f32_16x16x32_bf16 v[94:97], v[134:137], v[220:223], v[94:97]
	v_mfma_f32_16x16x32_bf16 v[90:93], v[138:141], v[212:215], v[90:93]
	v_mfma_f32_16x16x32_bf16 v[90:93], v[142:145], v[220:223], v[90:93]
	v_mfma_f32_16x16x32_bf16 v[86:89], v[162:165], v[212:215], v[86:89]
	v_mfma_f32_16x16x32_bf16 v[86:89], v[180:183], v[220:223], v[86:89]
	v_mfma_f32_16x16x32_bf16 v[82:85], v[184:187], v[212:215], v[82:85]
	v_mfma_f32_16x16x32_bf16 v[82:85], v[188:191], v[220:223], v[82:85]
	v_mfma_f32_16x16x32_bf16 v[66:69], v[184:187], v[224:227], v[66:69]
	v_mfma_f32_16x16x32_bf16 v[66:69], v[188:191], v[228:231], v[66:69]
	v_mfma_f32_16x16x32_bf16 v[70:73], v[162:165], v[224:227], v[70:73]
	v_mfma_f32_16x16x32_bf16 v[70:73], v[180:183], v[228:231], v[70:73]
	v_mfma_f32_16x16x32_bf16 v[74:77], v[138:141], v[224:227], v[74:77]
	v_mfma_f32_16x16x32_bf16 v[74:77], v[142:145], v[228:231], v[74:77]
	v_mfma_f32_16x16x32_bf16 v[78:81], v[130:133], v[224:227], v[78:81]
	v_mfma_f32_16x16x32_bf16 v[78:81], v[134:137], v[228:231], v[78:81]
	s_waitcnt vmcnt(8)
	s_barrier
	s_setprio 0
	ds_read_b128 v[196:199], v179 offset:49152
	ds_read_b128 v[200:203], v179 offset:50176
	ds_read_b128 v[204:207], v179 offset:51200
	ds_read_b128 v[208:211], v179 offset:52224
	ds_read_b128 v[212:215], v179 offset:53248
	ds_read_b128 v[220:223], v179 offset:54272
	ds_read_b128 v[224:227], v179 offset:55296
	ds_read_b128 v[228:231], v179 offset:56320
	s_add_u32 s60, s40, 0x80
	s_addc_u32 s61, s41, 0
	s_add_u32 vcc_lo, s60, 0x100000
	s_addc_u32 vcc_hi, s61, 0
	s_add_i32 m0, s24, 0x18000
	s_nop 0
	global_load_lds_dwordx4 v148, s[60:61]
	s_add_i32 m0, s24, 0x1a000
	s_nop 0
	global_load_lds_dwordx4 v152, s[60:61]
	s_add_i32 m0, s24, 0x1c000
	s_nop 0
	global_load_lds_dwordx4 v148, vcc
	s_add_i32 m0, s24, 0x1e000
	s_nop 0
	global_load_lds_dwordx4 v152, vcc
	s_add_u32 s60, s42, 0x80
	s_addc_u32 s61, s43, 0
	s_add_i32 m0, s24, 0x8000
	s_nop 0
	global_load_lds_dwordx4 v146, s[60:61]
	s_add_i32 m0, s24, 0xa000
	s_nop 0
	global_load_lds_dwordx4 v150, s[60:61]
	s_waitcnt lgkmcnt(0)
	s_setprio 1
	v_mfma_f32_16x16x32_bf16 v[62:65], v[130:133], v[196:199], v[62:65]
	v_mfma_f32_16x16x32_bf16 v[62:65], v[134:137], v[200:203], v[62:65]
	v_mfma_f32_16x16x32_bf16 v[58:61], v[138:141], v[196:199], v[58:61]
	v_mfma_f32_16x16x32_bf16 v[58:61], v[142:145], v[200:203], v[58:61]
	v_mfma_f32_16x16x32_bf16 v[54:57], v[162:165], v[196:199], v[54:57]
	v_mfma_f32_16x16x32_bf16 v[54:57], v[180:183], v[200:203], v[54:57]
	v_mfma_f32_16x16x32_bf16 v[50:53], v[184:187], v[196:199], v[50:53]
	v_mfma_f32_16x16x32_bf16 v[50:53], v[188:191], v[200:203], v[50:53]
	v_mfma_f32_16x16x32_bf16 v[34:37], v[184:187], v[204:207], v[34:37]
	v_mfma_f32_16x16x32_bf16 v[34:37], v[188:191], v[208:211], v[34:37]
	v_mfma_f32_16x16x32_bf16 v[38:41], v[162:165], v[204:207], v[38:41]
	v_mfma_f32_16x16x32_bf16 v[38:41], v[180:183], v[208:211], v[38:41]
	v_mfma_f32_16x16x32_bf16 v[42:45], v[138:141], v[204:207], v[42:45]
	v_mfma_f32_16x16x32_bf16 v[42:45], v[142:145], v[208:211], v[42:45]
	v_mfma_f32_16x16x32_bf16 v[46:49], v[130:133], v[204:207], v[46:49]
	v_mfma_f32_16x16x32_bf16 v[46:49], v[134:137], v[208:211], v[46:49]
	v_mfma_f32_16x16x32_bf16 v[30:33], v[130:133], v[212:215], v[30:33]
	v_mfma_f32_16x16x32_bf16 v[30:33], v[134:137], v[220:223], v[30:33]
	v_mfma_f32_16x16x32_bf16 v[26:29], v[138:141], v[212:215], v[26:29]
	v_mfma_f32_16x16x32_bf16 v[26:29], v[142:145], v[220:223], v[26:29]
	v_mfma_f32_16x16x32_bf16 v[22:25], v[162:165], v[212:215], v[22:25]
	v_mfma_f32_16x16x32_bf16 v[22:25], v[180:183], v[220:223], v[22:25]
	v_mfma_f32_16x16x32_bf16 v[18:21], v[184:187], v[212:215], v[18:21]
	v_mfma_f32_16x16x32_bf16 v[18:21], v[188:191], v[220:223], v[18:21]
	v_mfma_f32_16x16x32_bf16 v[2:5], v[184:187], v[224:227], v[2:5]
	v_mfma_f32_16x16x32_bf16 v[2:5], v[188:191], v[228:231], v[2:5]
	v_mfma_f32_16x16x32_bf16 v[6:9], v[162:165], v[224:227], v[6:9]
	v_mfma_f32_16x16x32_bf16 v[6:9], v[180:183], v[228:231], v[6:9]
	v_mfma_f32_16x16x32_bf16 v[10:13], v[138:141], v[224:227], v[10:13]
	v_mfma_f32_16x16x32_bf16 v[10:13], v[142:145], v[228:231], v[10:13]
	v_mfma_f32_16x16x32_bf16 v[14:17], v[130:133], v[224:227], v[14:17]
	v_mfma_f32_16x16x32_bf16 v[14:17], v[134:137], v[228:231], v[14:17]
	s_waitcnt vmcnt(8)
	s_barrier
	s_setprio 0
	s_add_i32 s58, s58, 2
	s_add_u32 s36, s36, 0x100
	s_addc_u32 s37, s37, 0
	s_add_u32 s56, s56, 0x100
	s_addc_u32 s57, s57, 0
	s_cmp_gt_u32 s58, 61
	s_cbranch_scc0 .LBB0_1251
	s_branch .Lf1_exit
; #define PG8_STAGE(bufoff, gbase, voff) do { _Pragma("unroll") for (int _i = 0; _i < 2; ++_i) \
;         __builtin_amdgcn_global_load_lds((const unsigned*)((const char*)(gbase) + (voff)[_i]), (PG8_LAS unsigned*)(lds + (bufoff) + ldsw + _i * 8192), 16, 0, 0); } while (0)
; #define PG8_LDA(dst, b, h) do { _Pragma("unroll") for (int m = 0; m < 4; ++m) _Pragma("unroll") for (int k = 0; k < 2; ++k) dst[m][k] = *(const PG8_LAS bf16x8*)(lds + PG8_SA(b, h) + aoff + m * 2048 + k * 1024); } while (0)
; #define PG8_LDB(dst, b, h) do { _Pragma("unroll") for (int n = 0; n < 2; ++n) _Pragma("unroll") for (int k = 0; k < 2; ++k) dst[n][k] = *(const PG8_LAS bf16x8*)(lds + PG8_SB(b, h) + boff + n * 2048 + k * 1024); } while (0)
; #define PG8_MMA(ai, bj, At, Bt) do { __builtin_amdgcn_s_setprio(1); _Pragma("unroll") for (int m = 0; m < 4; ++m) _Pragma("unroll") for (int n = 0; n < 2; ++n) _Pragma("unroll") for (int k = 0; k < 2; ++k) \
;         acc[ai][bj][m][n] = __builtin_amdgcn_mfma_f32_16x16x32_bf16(Bt[n][k], At[m][k], acc[ai][bj][m][n], 0, 0, 0); __builtin_amdgcn_s_setprio(0); } while (0)
; #define PG8_BAR __builtin_amdgcn_s_barrier()
; template <class Epi, class Sched, bool ALIGN_EPI = false, bool SP2 = false>
; __device__ __forceinline__ void gemm_phase(PG8_LAS unsigned char* lds, const Gemm g, const Sched& S, const Epi& E) {
;     ...
;             const bool last = (t == nt - 2);
;             const char* a1 = cA + (size_t)(t + 1) * kstep;
;             const char* a2 = last ? nA : cA + (size_t)(t + 2) * kstep; const char* b2 = last ? nB : cB + (size_t)(t + 2) * kstep;
;             const char* a3 = a2 + kstep; const char* b3 = b2 + kstep;
;             if (last && has_next) S.a_ready(nxt);
;             if constexpr (Epi::MIDK) { if (t == (nt >> 1)) { E.midk(acc, wr, fr); asm volatile("s_waitcnt lgkmcnt(0)" ::: "memory"); } }
;             if constexpr (SP2) {
;             PG8_LDB(B0, 0, 0); PG8_LDB(B1, 0, 1); PG8_SCHED; PG8_LDA(At, 0, 0); PG8_STAGE(PG8_SA(1, 1), a1 + hstep, voffA);
;             PG8_WAIT_V(8); PG8_WAIT_L(0); PG8_BAR; PG8_MMA(0, 0, At, B0); PG8_MMA(0, 1, At, B1); PG8_BAR; PG8_SCHED;
;             PG8_LDA(At, 0, 1); PG8_STAGE(PG8_SB(0, 0), b2, voffB); PG8_STAGE(PG8_SB(0, 1), b2 + hstep, voffB); PG8_STAGE(PG8_SA(0, 0), a2, voffA);
;             PG8_WAIT_V(8); PG8_WAIT_L(0); PG8_BAR; PG8_MMA(1, 0, At, B0); PG8_MMA(1, 1, At, B1); PG8_BAR; PG8_SCHED;
.Lf1_h1:
	ds_read_b128 v[130:133], v177
	ds_read_b128 v[134:137], v177 offset:1024
	ds_read_b128 v[138:141], v177 offset:2048
	ds_read_b128 v[142:145], v177 offset:3072
	ds_read_b128 v[162:165], v178
	ds_read_b128 v[180:183], v178 offset:1024
	ds_read_b128 v[184:187], v178 offset:2048
	ds_read_b128 v[188:191], v178 offset:3072
	s_add_u32 s40, s36, 0xfff00080
	s_addc_u32 s41, s37, -1
	s_cmp_eq_u32 s58, 60
	s_cselect_b32 s43, s15, s41
	s_cselect_b32 s42, s17, s40
	s_cselect_b32 s41, s54, s57
	s_cselect_b32 s40, s55, s56
	ds_read_b128 v[196:199], v179
	ds_read_b128 v[200:203], v179 offset:1024
	ds_read_b128 v[204:207], v179 offset:2048
	ds_read_b128 v[208:211], v179 offset:3072
	ds_read_b128 v[212:215], v179 offset:4096
	ds_read_b128 v[220:223], v179 offset:5120
	ds_read_b128 v[224:227], v179 offset:6144
	ds_read_b128 v[228:231], v179 offset:7168
	s_add_i32 m0, s24, 0xc000
	s_nop 0
	global_load_lds_dwordx4 v146, s[36:37]
	s_add_i32 m0, s24, 0xe000
	s_nop 0
	global_load_lds_dwordx4 v150, s[36:37]
	s_sleep 2
	s_waitcnt lgkmcnt(0)
	s_setprio 2
	s_waitcnt vmcnt(8)
	s_barrier
	v_mfma_f32_16x16x32_bf16 v[126:129], v[130:133], v[196:199], v[126:129]
	v_mfma_f32_16x16x32_bf16 v[126:129], v[134:137], v[200:203], v[126:129]
	v_mfma_f32_16x16x32_bf16 v[122:125], v[138:141], v[196:199], v[122:125]
	v_mfma_f32_16x16x32_bf16 v[122:125], v[142:145], v[200:203], v[122:125]
	v_mfma_f32_16x16x32_bf16 v[118:121], v[162:165], v[196:199], v[118:121]
	v_mfma_f32_16x16x32_bf16 v[118:121], v[180:183], v[200:203], v[118:121]
	v_mfma_f32_16x16x32_bf16 v[114:117], v[184:187], v[196:199], v[114:117]
	v_mfma_f32_16x16x32_bf16 v[114:117], v[188:191], v[200:203], v[114:117]
	v_mfma_f32_16x16x32_bf16 v[98:101], v[184:187], v[204:207], v[98:101]
	v_mfma_f32_16x16x32_bf16 v[98:101], v[188:191], v[208:211], v[98:101]
	v_mfma_f32_16x16x32_bf16 v[102:105], v[162:165], v[204:207], v[102:105]
	v_mfma_f32_16x16x32_bf16 v[102:105], v[180:183], v[208:211], v[102:105]
	v_mfma_f32_16x16x32_bf16 v[106:109], v[138:141], v[204:207], v[106:109]
	v_mfma_f32_16x16x32_bf16 v[106:109], v[142:145], v[208:211], v[106:109]
	v_mfma_f32_16x16x32_bf16 v[110:113], v[130:133], v[204:207], v[110:113]
	v_mfma_f32_16x16x32_bf16 v[110:113], v[134:137], v[208:211], v[110:113]
	v_mfma_f32_16x16x32_bf16 v[94:97], v[130:133], v[212:215], v[94:97]
	v_mfma_f32_16x16x32_bf16 v[94:97], v[134:137], v[220:223], v[94:97]
	v_mfma_f32_16x16x32_bf16 v[90:93], v[138:141], v[212:215], v[90:93]
	v_mfma_f32_16x16x32_bf16 v[90:93], v[142:145], v[220:223], v[90:93]
	v_mfma_f32_16x16x32_bf16 v[86:89], v[162:165], v[212:215], v[86:89]
	v_mfma_f32_16x16x32_bf16 v[86:89], v[180:183], v[220:223], v[86:89]
	v_mfma_f32_16x16x32_bf16 v[82:85], v[184:187], v[212:215], v[82:85]
	v_mfma_f32_16x16x32_bf16 v[82:85], v[188:191], v[220:223], v[82:85]
	v_mfma_f32_16x16x32_bf16 v[66:69], v[184:187], v[224:227], v[66:69]
	v_mfma_f32_16x16x32_bf16 v[66:69], v[188:191], v[228:231], v[66:69]
	v_mfma_f32_16x16x32_bf16 v[70:73], v[162:165], v[224:227], v[70:73]
	v_mfma_f32_16x16x32_bf16 v[70:73], v[180:183], v[228:231], v[70:73]
	v_mfma_f32_16x16x32_bf16 v[74:77], v[138:141], v[224:227], v[74:77]
	v_mfma_f32_16x16x32_bf16 v[74:77], v[142:145], v[228:231], v[74:77]
	v_mfma_f32_16x16x32_bf16 v[78:81], v[130:133], v[224:227], v[78:81]
	v_mfma_f32_16x16x32_bf16 v[78:81], v[134:137], v[228:231], v[78:81]
	s_setprio 0
	ds_read_b128 v[196:199], v179 offset:16384
	ds_read_b128 v[200:203], v179 offset:17408
	ds_read_b128 v[204:207], v179 offset:18432
	ds_read_b128 v[208:211], v179 offset:19456
	ds_read_b128 v[212:215], v179 offset:20480
	ds_read_b128 v[220:223], v179 offset:21504
	ds_read_b128 v[224:227], v179 offset:22528
	ds_read_b128 v[228:231], v179 offset:23552
	s_add_u32 vcc_lo, s40, 0x100000
	s_addc_u32 vcc_hi, s41, 0
	s_add_i32 m0, s24, 0x10000
	s_nop 0
	global_load_lds_dwordx4 v148, s[40:41]
	s_add_i32 m0, s24, 0x12000
	s_nop 0
	global_load_lds_dwordx4 v152, s[40:41]
	s_add_i32 m0, s24, 0x14000
	s_nop 0
	global_load_lds_dwordx4 v148, vcc
	s_add_i32 m0, s24, 0x16000
	s_nop 0
	global_load_lds_dwordx4 v152, vcc
	s_mov_b32 m0, s24
	s_nop 0
	global_load_lds_dwordx4 v146, s[42:43]
	s_add_i32 m0, s24, 0x2000
	s_nop 0
	global_load_lds_dwordx4 v150, s[42:43]
	s_sleep 2
	s_waitcnt lgkmcnt(0)
	s_setprio 2
	s_waitcnt vmcnt(8)
	s_barrier
; #define PG8_STAGE(bufoff, gbase, voff) do { _Pragma("unroll") for (int _i = 0; _i < 2; ++_i) \
;         __builtin_amdgcn_global_load_lds((const unsigned*)((const char*)(gbase) + (voff)[_i]), (PG8_LAS unsigned*)(lds + (bufoff) + ldsw + _i * 8192), 16, 0, 0); } while (0)
; #define PG8_LDA(dst, b, h) do { _Pragma("unroll") for (int m = 0; m < 4; ++m) _Pragma("unroll") for (int k = 0; k < 2; ++k) dst[m][k] = *(const PG8_LAS bf16x8*)(lds + PG8_SA(b, h) + aoff + m * 2048 + k * 1024); } while (0)
; #define PG8_LDB(dst, b, h) do { _Pragma("unroll") for (int n = 0; n < 2; ++n) _Pragma("unroll") for (int k = 0; k < 2; ++k) dst[n][k] = *(const PG8_LAS bf16x8*)(lds + PG8_SB(b, h) + boff + n * 2048 + k * 1024); } while (0)
; #define PG8_MMA(ai, bj, At, Bt) do { __builtin_amdgcn_s_setprio(1); _Pragma("unroll") for (int m = 0; m < 4; ++m) _Pragma("unroll") for (int n = 0; n < 2; ++n) _Pragma("unroll") for (int k = 0; k < 2; ++k) \
;         acc[ai][bj][m][n] = __builtin_amdgcn_mfma_f32_16x16x32_bf16(Bt[n][k], At[m][k], acc[ai][bj][m][n], 0, 0, 0); __builtin_amdgcn_s_setprio(0); } while (0)
; #define PG8_WAIT_V(n) asm volatile("s_waitcnt vmcnt(" #n ")" ::: "memory")
; #define PG8_WAIT_L(n) asm volatile("s_waitcnt lgkmcnt(" #n ")" ::: "memory")
; #define PG8_BAR __builtin_amdgcn_s_barrier()
; #define PG8_SCHED __builtin_amdgcn_sched_barrier(0)
; template <class Epi, class Sched, bool ALIGN_EPI = false, bool SP2 = false>
; __device__ __forceinline__ void gemm_phase(PG8_LAS unsigned char* lds, const Gemm g, const Sched& S, const Epi& E) {
;     ...
;             PG8_WAIT_V(8); PG8_WAIT_L(0); PG8_BAR; PG8_MMA(1, 0, At, B0); PG8_MMA(1, 1, At, B1); PG8_BAR; PG8_SCHED;
;             PG8_LDB(B0, 1, 0); PG8_LDB(B1, 1, 1); PG8_SCHED; PG8_LDA(At, 1, 0); PG8_STAGE(PG8_SA(0, 1), a2 + hstep, voffA);
;             PG8_WAIT_V(8); PG8_WAIT_L(0); PG8_BAR; PG8_MMA(0, 0, At, B0); PG8_MMA(0, 1, At, B1); PG8_BAR; PG8_SCHED;
	v_mfma_f32_16x16x32_bf16 v[62:65], v[130:133], v[196:199], v[62:65]
	v_mfma_f32_16x16x32_bf16 v[62:65], v[134:137], v[200:203], v[62:65]
	v_mfma_f32_16x16x32_bf16 v[58:61], v[138:141], v[196:199], v[58:61]
	v_mfma_f32_16x16x32_bf16 v[58:61], v[142:145], v[200:203], v[58:61]
	v_mfma_f32_16x16x32_bf16 v[54:57], v[162:165], v[196:199], v[54:57]
	v_mfma_f32_16x16x32_bf16 v[54:57], v[180:183], v[200:203], v[54:57]
	v_mfma_f32_16x16x32_bf16 v[50:53], v[184:187], v[196:199], v[50:53]
	v_mfma_f32_16x16x32_bf16 v[50:53], v[188:191], v[200:203], v[50:53]
	v_mfma_f32_16x16x32_bf16 v[34:37], v[184:187], v[204:207], v[34:37]
	v_mfma_f32_16x16x32_bf16 v[34:37], v[188:191], v[208:211], v[34:37]
	v_mfma_f32_16x16x32_bf16 v[38:41], v[162:165], v[204:207], v[38:41]
	v_mfma_f32_16x16x32_bf16 v[38:41], v[180:183], v[208:211], v[38:41]
	v_mfma_f32_16x16x32_bf16 v[42:45], v[138:141], v[204:207], v[42:45]
	v_mfma_f32_16x16x32_bf16 v[42:45], v[142:145], v[208:211], v[42:45]
	v_mfma_f32_16x16x32_bf16 v[46:49], v[130:133], v[204:207], v[46:49]
	v_mfma_f32_16x16x32_bf16 v[46:49], v[134:137], v[208:211], v[46:49]
	v_mfma_f32_16x16x32_bf16 v[30:33], v[130:133], v[212:215], v[30:33]
	v_mfma_f32_16x16x32_bf16 v[30:33], v[134:137], v[220:223], v[30:33]
	v_mfma_f32_16x16x32_bf16 v[26:29], v[138:141], v[212:215], v[26:29]
	v_mfma_f32_16x16x32_bf16 v[26:29], v[142:145], v[220:223], v[26:29]
	v_mfma_f32_16x16x32_bf16 v[22:25], v[162:165], v[212:215], v[22:25]
	v_mfma_f32_16x16x32_bf16 v[22:25], v[180:183], v[220:223], v[22:25]
	v_mfma_f32_16x16x32_bf16 v[18:21], v[184:187], v[212:215], v[18:21]
	v_mfma_f32_16x16x32_bf16 v[18:21], v[188:191], v[220:223], v[18:21]
	v_mfma_f32_16x16x32_bf16 v[2:5], v[184:187], v[224:227], v[2:5]
	v_mfma_f32_16x16x32_bf16 v[2:5], v[188:191], v[228:231], v[2:5]
	v_mfma_f32_16x16x32_bf16 v[6:9], v[162:165], v[224:227], v[6:9]
	v_mfma_f32_16x16x32_bf16 v[6:9], v[180:183], v[228:231], v[6:9]
	v_mfma_f32_16x16x32_bf16 v[10:13], v[138:141], v[224:227], v[10:13]
	v_mfma_f32_16x16x32_bf16 v[10:13], v[142:145], v[228:231], v[10:13]
	v_mfma_f32_16x16x32_bf16 v[14:17], v[130:133], v[224:227], v[14:17]
	v_mfma_f32_16x16x32_bf16 v[14:17], v[134:137], v[228:231], v[14:17]
	s_setprio 0
	s_add_i32 s59, 0, 0x18000
	s_add_i32 s60, 0, 0x1c000
	v_add_u32_e32 v142, s59, v166
	v_add_u32_e32 v188, s60, v166
	ds_read_b128 v[130:133], v142
	ds_read_b128 v[134:137], v142 offset:1024
	ds_read_b128 v[138:141], v142 offset:2048
	ds_read_b128 v[142:145], v142 offset:3072
	ds_read_b128 v[162:165], v188
	ds_read_b128 v[180:183], v188 offset:1024
	ds_read_b128 v[184:187], v188 offset:2048
	ds_read_b128 v[188:191], v188 offset:3072
	ds_read_b128 v[196:199], v179 offset:32768
	ds_read_b128 v[200:203], v179 offset:33792
	ds_read_b128 v[204:207], v179 offset:34816
	ds_read_b128 v[208:211], v179 offset:35840
	ds_read_b128 v[212:215], v179 offset:36864
	ds_read_b128 v[220:223], v179 offset:37888
	ds_read_b128 v[224:227], v179 offset:38912
	ds_read_b128 v[228:231], v179 offset:39936
	s_add_u32 vcc_lo, s42, 0x100000
	s_addc_u32 vcc_hi, s43, 0
	s_add_i32 m0, s24, 0x4000
	s_nop 0
	global_load_lds_dwordx4 v146, vcc
	s_add_i32 m0, s24, 0x6000
	s_nop 0
	global_load_lds_dwordx4 v150, vcc
	s_sleep 2
	s_waitcnt lgkmcnt(0)
	s_setprio 2
	s_waitcnt vmcnt(8)
	s_barrier
; #define PG8_STAGE(bufoff, gbase, voff) do { _Pragma("unroll") for (int _i = 0; _i < 2; ++_i) \
;         __builtin_amdgcn_global_load_lds((const unsigned*)((const char*)(gbase) + (voff)[_i]), (PG8_LAS unsigned*)(lds + (bufoff) + ldsw + _i * 8192), 16, 0, 0); } while (0)
; #define PG8_LDA(dst, b, h) do { _Pragma("unroll") for (int m = 0; m < 4; ++m) _Pragma("unroll") for (int k = 0; k < 2; ++k) dst[m][k] = *(const PG8_LAS bf16x8*)(lds + PG8_SA(b, h) + aoff + m * 2048 + k * 1024); } while (0)
; #define PG8_WAIT_V(n) asm volatile("s_waitcnt vmcnt(" #n ")" ::: "memory")
; template <class Epi, class Sched, bool ALIGN_EPI = false, bool SP2 = false>
; __device__ __forceinline__ void gemm_phase(PG8_LAS unsigned char* lds, const Gemm g, const Sched& S, const Epi& E) {
;     ...
;         for (int t = 0; t < nt; t += 2) {
;             const bool last = (t == nt - 2);
;             const char* a1 = cA + (size_t)(t + 1) * kstep;
;             const char* a2 = last ? nA : cA + (size_t)(t + 2) * kstep; const char* b2 = last ? nB : cB + (size_t)(t + 2) * kstep;
;             const char* a3 = a2 + kstep; const char* b3 = b2 + kstep;
;             if (last && has_next) S.a_ready(nxt);
;             if constexpr (Epi::MIDK) { if (t == (nt >> 1)) { E.midk(acc, wr, fr); asm volatile("s_waitcnt lgkmcnt(0)" ::: "memory"); } }
;             if constexpr (SP2) {
;             PG8_LDB(B0, 0, 0); PG8_LDB(B1, 0, 1); PG8_SCHED; PG8_LDA(At, 0, 0); PG8_STAGE(PG8_SA(1, 1), a1 + hstep, voffA);
;             PG8_WAIT_V(8); PG8_WAIT_L(0); PG8_BAR; PG8_MMA(0, 0, At, B0); PG8_MMA(0, 1, At, B1); PG8_BAR; PG8_SCHED;
;             PG8_LDA(At, 0, 1); PG8_STAGE(PG8_SB(0, 0), b2, voffB); PG8_STAGE(PG8_SB(0, 1), b2 + hstep, voffB); PG8_STAGE(PG8_SA(0, 0), a2, voffA);
;             PG8_WAIT_V(8); PG8_WAIT_L(0); PG8_BAR; PG8_MMA(1, 0, At, B0); PG8_MMA(1, 1, At, B1); PG8_BAR; PG8_SCHED;
;             PG8_LDB(B0, 1, 0); PG8_LDB(B1, 1, 1); PG8_SCHED; PG8_LDA(At, 1, 0); PG8_STAGE(PG8_SA(0, 1), a2 + hstep, voffA);
;             PG8_WAIT_V(8); PG8_WAIT_L(0); PG8_BAR; PG8_MMA(0, 0, At, B0); PG8_MMA(0, 1, At, B1); PG8_BAR; PG8_SCHED;
;             PG8_LDA(At, 1, 1); PG8_STAGE(PG8_SB(1, 0), b3, voffB); PG8_STAGE(PG8_SB(1, 1), b3 + hstep, voffB); PG8_STAGE(PG8_SA(1, 0), a3, voffA);
;             PG8_WAIT_V(8); PG8_WAIT_L(0); PG8_BAR; PG8_MMA(1, 0, At, B0); PG8_MMA(1, 1, At, B1); PG8_BAR; PG8_SCHED;
	v_mfma_f32_16x16x32_bf16 v[126:129], v[130:133], v[196:199], v[126:129]
	v_mfma_f32_16x16x32_bf16 v[126:129], v[134:137], v[200:203], v[126:129]
	v_mfma_f32_16x16x32_bf16 v[122:125], v[138:141], v[196:199], v[122:125]
	v_mfma_f32_16x16x32_bf16 v[122:125], v[142:145], v[200:203], v[122:125]
	v_mfma_f32_16x16x32_bf16 v[118:121], v[162:165], v[196:199], v[118:121]
	v_mfma_f32_16x16x32_bf16 v[118:121], v[180:183], v[200:203], v[118:121]
	v_mfma_f32_16x16x32_bf16 v[114:117], v[184:187], v[196:199], v[114:117]
	v_mfma_f32_16x16x32_bf16 v[114:117], v[188:191], v[200:203], v[114:117]
	v_mfma_f32_16x16x32_bf16 v[98:101], v[184:187], v[204:207], v[98:101]
	v_mfma_f32_16x16x32_bf16 v[98:101], v[188:191], v[208:211], v[98:101]
	v_mfma_f32_16x16x32_bf16 v[102:105], v[162:165], v[204:207], v[102:105]
	v_mfma_f32_16x16x32_bf16 v[102:105], v[180:183], v[208:211], v[102:105]
	v_mfma_f32_16x16x32_bf16 v[106:109], v[138:141], v[204:207], v[106:109]
	v_mfma_f32_16x16x32_bf16 v[106:109], v[142:145], v[208:211], v[106:109]
	v_mfma_f32_16x16x32_bf16 v[110:113], v[130:133], v[204:207], v[110:113]
	v_mfma_f32_16x16x32_bf16 v[110:113], v[134:137], v[208:211], v[110:113]
	v_mfma_f32_16x16x32_bf16 v[94:97], v[130:133], v[212:215], v[94:97]
	v_mfma_f32_16x16x32_bf16 v[94:97], v[134:137], v[220:223], v[94:97]
	v_mfma_f32_16x16x32_bf16 v[90:93], v[138:141], v[212:215], v[90:93]
	v_mfma_f32_16x16x32_bf16 v[90:93], v[142:145], v[220:223], v[90:93]
	v_mfma_f32_16x16x32_bf16 v[86:89], v[162:165], v[212:215], v[86:89]
	v_mfma_f32_16x16x32_bf16 v[86:89], v[180:183], v[220:223], v[86:89]
	v_mfma_f32_16x16x32_bf16 v[82:85], v[184:187], v[212:215], v[82:85]
	v_mfma_f32_16x16x32_bf16 v[82:85], v[188:191], v[220:223], v[82:85]
	v_mfma_f32_16x16x32_bf16 v[66:69], v[184:187], v[224:227], v[66:69]
	v_mfma_f32_16x16x32_bf16 v[66:69], v[188:191], v[228:231], v[66:69]
	v_mfma_f32_16x16x32_bf16 v[70:73], v[162:165], v[224:227], v[70:73]
	v_mfma_f32_16x16x32_bf16 v[70:73], v[180:183], v[228:231], v[70:73]
	v_mfma_f32_16x16x32_bf16 v[74:77], v[138:141], v[224:227], v[74:77]
	v_mfma_f32_16x16x32_bf16 v[74:77], v[142:145], v[228:231], v[74:77]
	v_mfma_f32_16x16x32_bf16 v[78:81], v[130:133], v[224:227], v[78:81]
	v_mfma_f32_16x16x32_bf16 v[78:81], v[134:137], v[228:231], v[78:81]
	s_setprio 0
	ds_read_b128 v[196:199], v179 offset:49152
	ds_read_b128 v[200:203], v179 offset:50176
	ds_read_b128 v[204:207], v179 offset:51200
	ds_read_b128 v[208:211], v179 offset:52224
	ds_read_b128 v[212:215], v179 offset:53248
	ds_read_b128 v[220:223], v179 offset:54272
	ds_read_b128 v[224:227], v179 offset:55296
	ds_read_b128 v[228:231], v179 offset:56320
	s_add_u32 s60, s40, 0x80
	s_addc_u32 s61, s41, 0
	s_add_u32 vcc_lo, s60, 0x100000
	s_addc_u32 vcc_hi, s61, 0
	s_add_i32 m0, s24, 0x18000
	s_nop 0
	global_load_lds_dwordx4 v148, s[60:61]
	s_add_i32 m0, s24, 0x1a000
	s_nop 0
	global_load_lds_dwordx4 v152, s[60:61]
	s_add_i32 m0, s24, 0x1c000
	s_nop 0
	global_load_lds_dwordx4 v148, vcc
	s_add_i32 m0, s24, 0x1e000
	s_nop 0
	global_load_lds_dwordx4 v152, vcc
	s_add_u32 s60, s42, 0x80
	s_addc_u32 s61, s43, 0
	s_add_i32 m0, s24, 0x8000
	s_nop 0
	global_load_lds_dwordx4 v146, s[60:61]
	s_add_i32 m0, s24, 0xa000
	s_nop 0
	global_load_lds_dwordx4 v150, s[60:61]
	s_sleep 2
	s_waitcnt lgkmcnt(0)
	s_setprio 2
	s_waitcnt vmcnt(8)
	s_barrier
	v_mfma_f32_16x16x32_bf16 v[62:65], v[130:133], v[196:199], v[62:65]
	v_mfma_f32_16x16x32_bf16 v[62:65], v[134:137], v[200:203], v[62:65]
	v_mfma_f32_16x16x32_bf16 v[58:61], v[138:141], v[196:199], v[58:61]
	v_mfma_f32_16x16x32_bf16 v[58:61], v[142:145], v[200:203], v[58:61]
	v_mfma_f32_16x16x32_bf16 v[54:57], v[162:165], v[196:199], v[54:57]
	v_mfma_f32_16x16x32_bf16 v[54:57], v[180:183], v[200:203], v[54:57]
	v_mfma_f32_16x16x32_bf16 v[50:53], v[184:187], v[196:199], v[50:53]
	v_mfma_f32_16x16x32_bf16 v[50:53], v[188:191], v[200:203], v[50:53]
	v_mfma_f32_16x16x32_bf16 v[34:37], v[184:187], v[204:207], v[34:37]
	v_mfma_f32_16x16x32_bf16 v[34:37], v[188:191], v[208:211], v[34:37]
	v_mfma_f32_16x16x32_bf16 v[38:41], v[162:165], v[204:207], v[38:41]
	v_mfma_f32_16x16x32_bf16 v[38:41], v[180:183], v[208:211], v[38:41]
	v_mfma_f32_16x16x32_bf16 v[42:45], v[138:141], v[204:207], v[42:45]
	v_mfma_f32_16x16x32_bf16 v[42:45], v[142:145], v[208:211], v[42:45]
	v_mfma_f32_16x16x32_bf16 v[46:49], v[130:133], v[204:207], v[46:49]
	v_mfma_f32_16x16x32_bf16 v[46:49], v[134:137], v[208:211], v[46:49]
	v_mfma_f32_16x16x32_bf16 v[30:33], v[130:133], v[212:215], v[30:33]
	v_mfma_f32_16x16x32_bf16 v[30:33], v[134:137], v[220:223], v[30:33]
	v_mfma_f32_16x16x32_bf16 v[26:29], v[138:141], v[212:215], v[26:29]
	v_mfma_f32_16x16x32_bf16 v[26:29], v[142:145], v[220:223], v[26:29]
	v_mfma_f32_16x16x32_bf16 v[22:25], v[162:165], v[212:215], v[22:25]
	v_mfma_f32_16x16x32_bf16 v[22:25], v[180:183], v[220:223], v[22:25]
	v_mfma_f32_16x16x32_bf16 v[18:21], v[184:187], v[212:215], v[18:21]
	v_mfma_f32_16x16x32_bf16 v[18:21], v[188:191], v[220:223], v[18:21]
	v_mfma_f32_16x16x32_bf16 v[2:5], v[184:187], v[224:227], v[2:5]
	v_mfma_f32_16x16x32_bf16 v[2:5], v[188:191], v[228:231], v[2:5]
	v_mfma_f32_16x16x32_bf16 v[6:9], v[162:165], v[224:227], v[6:9]
	v_mfma_f32_16x16x32_bf16 v[6:9], v[180:183], v[228:231], v[6:9]
	v_mfma_f32_16x16x32_bf16 v[10:13], v[138:141], v[224:227], v[10:13]
	v_mfma_f32_16x16x32_bf16 v[10:13], v[142:145], v[228:231], v[10:13]
	v_mfma_f32_16x16x32_bf16 v[14:17], v[130:133], v[224:227], v[14:17]
	v_mfma_f32_16x16x32_bf16 v[14:17], v[134:137], v[228:231], v[14:17]
	s_setprio 0
	s_add_i32 s58, s58, 2
	s_add_u32 s36, s36, 0x100
	s_addc_u32 s37, s37, 0
	s_add_u32 s56, s56, 0x100
	s_addc_u32 s57, s57, 0
	s_cmp_gt_u32 s58, 61
	s_cbranch_scc0 .Lf1_h1

; #define PG8_STAGE(bufoff, gbase, voff) do { _Pragma("unroll") for (int _i = 0; _i < 2; ++_i) \
;         __builtin_amdgcn_global_load_lds((const unsigned*)((const char*)(gbase) + (voff)[_i]), (PG8_LAS unsigned*)(lds + (bufoff) + ldsw + _i * 8192), 16, 0, 0); } while (0)
; #define PG8_LDA(dst, b, h) do { _Pragma("unroll") for (int m = 0; m < 4; ++m) _Pragma("unroll") for (int k = 0; k < 2; ++k) dst[m][k] = *(const PG8_LAS bf16x8*)(lds + PG8_SA(b, h) + aoff + m * 2048 + k * 1024); } while (0)
; #define PG8_LDB(dst, b, h) do { _Pragma("unroll") for (int n = 0; n < 2; ++n) _Pragma("unroll") for (int k = 0; k < 2; ++k) dst[n][k] = *(const PG8_LAS bf16x8*)(lds + PG8_SB(b, h) + boff + n * 2048 + k * 1024); } while (0)
; #define PG8_MMA(ai, bj, At, Bt) do { __builtin_amdgcn_s_setprio(1); _Pragma("unroll") for (int m = 0; m < 4; ++m) _Pragma("unroll") for (int n = 0; n < 2; ++n) _Pragma("unroll") for (int k = 0; k < 2; ++k) \
;         acc[ai][bj][m][n] = __builtin_amdgcn_mfma_f32_16x16x32_bf16(Bt[n][k], At[m][k], acc[ai][bj][m][n], 0, 0, 0); __builtin_amdgcn_s_setprio(0); } while (0)
; #define PG8_BAR __builtin_amdgcn_s_barrier()
; template <class Epi, class Sched, bool ALIGN_EPI = false, bool SP2 = false>
; __device__ __forceinline__ void gemm_phase(PG8_LAS unsigned char* lds, const Gemm g, const Sched& S, const Epi& E) {
;     ...
;             const bool last = (t == nt - 2);
;             const char* a1 = cA + (size_t)(t + 1) * kstep;
;             const char* a2 = last ? nA : cA + (size_t)(t + 2) * kstep; const char* b2 = last ? nB : cB + (size_t)(t + 2) * kstep;
;             const char* a3 = a2 + kstep; const char* b3 = b2 + kstep;
;             if (last && has_next) S.a_ready(nxt);
;             if constexpr (Epi::MIDK) { if (t == (nt >> 1)) { E.midk(acc, wr, fr); asm volatile("s_waitcnt lgkmcnt(0)" ::: "memory"); } }
;             if constexpr (SP2) {
;             PG8_LDB(B0, 0, 0); PG8_LDB(B1, 0, 1); PG8_SCHED; PG8_LDA(At, 0, 0); PG8_STAGE(PG8_SA(1, 1), a1 + hstep, voffA);
;             PG8_WAIT_V(8); PG8_WAIT_L(0); PG8_BAR; PG8_MMA(0, 0, At, B0); PG8_MMA(0, 1, At, B1); PG8_BAR; PG8_SCHED;
;             PG8_LDA(At, 0, 1); PG8_STAGE(PG8_SB(0, 0), b2, voffB); PG8_STAGE(PG8_SB(0, 1), b2 + hstep, voffB); PG8_STAGE(PG8_SA(0, 0), a2, voffA);
;             PG8_WAIT_V(8); PG8_WAIT_L(0); PG8_BAR; PG8_MMA(1, 0, At, B0); PG8_MMA(1, 1, At, B1); PG8_BAR; PG8_SCHED;
.LBB0_1321:
	ds_read_b128 v[128:131], v156
	ds_read_b128 v[132:135], v156 offset:1024
	ds_read_b128 v[150:153], v156 offset:2048
	ds_read_b128 v[162:165], v156 offset:3072
	ds_read_b128 v[166:169], v157
	ds_read_b128 v[170:173], v157 offset:1024
	ds_read_b128 v[174:177], v157 offset:2048
	ds_read_b128 v[178:181], v157 offset:3072
	s_add_u32 s20, s18, 0xffbfc080
	s_addc_u32 s21, s19, -1
	s_cmpk_eq_i32 s59, 0xfc
	s_cselect_b32 s23, s7, s21
	s_cselect_b32 s22, s6, s20
	s_cselect_b32 s21, s17, s58
	s_cselect_b32 s20, s16, s57
	ds_read_b128 v[182:185], v158
	ds_read_b128 v[186:189], v158 offset:1024
	ds_read_b128 v[190:193], v158 offset:2048
	ds_read_b128 v[194:197], v158 offset:3072
	ds_read_b128 v[198:201], v158 offset:4096
	ds_read_b128 v[202:205], v158 offset:5120
	ds_read_b128 v[206:209], v158 offset:6144
	ds_read_b128 v[210:213], v158 offset:7168
	s_add_i32 m0, s24, 0xc000
	s_nop 0
	global_load_lds_dwordx4 v136, s[18:19]
	s_add_i32 m0, s24, 0xe000
	s_nop 0
	global_load_lds_dwordx4 v140, s[18:19]
	s_waitcnt lgkmcnt(0)
	s_setprio 1
	v_mfma_f32_16x16x32_bf16 v[124:127], v[128:131], v[182:185], v[124:127]
	v_mfma_f32_16x16x32_bf16 v[124:127], v[132:135], v[186:189], v[124:127]
	v_mfma_f32_16x16x32_bf16 v[120:123], v[150:153], v[182:185], v[120:123]
	v_mfma_f32_16x16x32_bf16 v[120:123], v[162:165], v[186:189], v[120:123]
	v_mfma_f32_16x16x32_bf16 v[68:71], v[166:169], v[182:185], v[68:71]
	v_mfma_f32_16x16x32_bf16 v[68:71], v[170:173], v[186:189], v[68:71]
	v_mfma_f32_16x16x32_bf16 v[64:67], v[174:177], v[182:185], v[64:67]
	v_mfma_f32_16x16x32_bf16 v[64:67], v[178:181], v[186:189], v[64:67]
	v_mfma_f32_16x16x32_bf16 v[48:51], v[174:177], v[190:193], v[48:51]
	v_mfma_f32_16x16x32_bf16 v[48:51], v[178:181], v[194:197], v[48:51]
	v_mfma_f32_16x16x32_bf16 v[52:55], v[166:169], v[190:193], v[52:55]
	v_mfma_f32_16x16x32_bf16 v[52:55], v[170:173], v[194:197], v[52:55]
	v_mfma_f32_16x16x32_bf16 v[112:115], v[150:153], v[190:193], v[112:115]
	v_mfma_f32_16x16x32_bf16 v[112:115], v[162:165], v[194:197], v[112:115]
	v_mfma_f32_16x16x32_bf16 v[116:119], v[128:131], v[190:193], v[116:119]
	v_mfma_f32_16x16x32_bf16 v[116:119], v[132:135], v[194:197], v[116:119]
	v_mfma_f32_16x16x32_bf16 v[108:111], v[128:131], v[198:201], v[108:111]
	v_mfma_f32_16x16x32_bf16 v[108:111], v[132:135], v[202:205], v[108:111]
	v_mfma_f32_16x16x32_bf16 v[104:107], v[150:153], v[198:201], v[104:107]
	v_mfma_f32_16x16x32_bf16 v[104:107], v[162:165], v[202:205], v[104:107]
	v_mfma_f32_16x16x32_bf16 v[44:47], v[166:169], v[198:201], v[44:47]
	v_mfma_f32_16x16x32_bf16 v[44:47], v[170:173], v[202:205], v[44:47]
	v_mfma_f32_16x16x32_bf16 v[40:43], v[174:177], v[198:201], v[40:43]
	v_mfma_f32_16x16x32_bf16 v[40:43], v[178:181], v[202:205], v[40:43]
	v_mfma_f32_16x16x32_bf16 v[32:35], v[174:177], v[206:209], v[32:35]
	v_mfma_f32_16x16x32_bf16 v[32:35], v[178:181], v[210:213], v[32:35]
	v_mfma_f32_16x16x32_bf16 v[36:39], v[166:169], v[206:209], v[36:39]
	v_mfma_f32_16x16x32_bf16 v[36:39], v[170:173], v[210:213], v[36:39]
	v_mfma_f32_16x16x32_bf16 v[96:99], v[150:153], v[206:209], v[96:99]
	v_mfma_f32_16x16x32_bf16 v[96:99], v[162:165], v[210:213], v[96:99]
	v_mfma_f32_16x16x32_bf16 v[100:103], v[128:131], v[206:209], v[100:103]
	v_mfma_f32_16x16x32_bf16 v[100:103], v[132:135], v[210:213], v[100:103]
	s_waitcnt vmcnt(8)
	s_barrier
	s_setprio 0
	ds_read_b128 v[182:185], v158 offset:16384
	ds_read_b128 v[186:189], v158 offset:17408
	ds_read_b128 v[190:193], v158 offset:18432
	ds_read_b128 v[194:197], v158 offset:19456
	ds_read_b128 v[198:201], v158 offset:20480
	ds_read_b128 v[202:205], v158 offset:21504
	ds_read_b128 v[206:209], v158 offset:22528
	ds_read_b128 v[210:213], v158 offset:23552
	s_add_u32 vcc_lo, s20, 0x404000
	s_addc_u32 vcc_hi, s21, 0
	s_add_i32 m0, s24, 0x10000
	s_nop 0
	global_load_lds_dwordx4 v138, s[20:21]
	s_add_i32 m0, s24, 0x12000
	s_nop 0
	global_load_lds_dwordx4 v142, s[20:21]
	s_add_i32 m0, s24, 0x14000
	s_nop 0
	global_load_lds_dwordx4 v138, vcc
	s_add_i32 m0, s24, 0x16000
	s_nop 0
	global_load_lds_dwordx4 v142, vcc
	s_mov_b32 m0, s24
	s_nop 0
	global_load_lds_dwordx4 v136, s[22:23]
	s_add_i32 m0, s24, 0x2000
	s_nop 0
	global_load_lds_dwordx4 v140, s[22:23]
	s_waitcnt lgkmcnt(0)
	s_setprio 1
	v_mfma_f32_16x16x32_bf16 v[92:95], v[128:131], v[182:185], v[92:95]
	v_mfma_f32_16x16x32_bf16 v[92:95], v[132:135], v[186:189], v[92:95]
	v_mfma_f32_16x16x32_bf16 v[88:91], v[150:153], v[182:185], v[88:91]
	v_mfma_f32_16x16x32_bf16 v[88:91], v[162:165], v[186:189], v[88:91]
	v_mfma_f32_16x16x32_bf16 v[28:31], v[166:169], v[182:185], v[28:31]
	v_mfma_f32_16x16x32_bf16 v[28:31], v[170:173], v[186:189], v[28:31]
	v_mfma_f32_16x16x32_bf16 v[24:27], v[174:177], v[182:185], v[24:27]
	v_mfma_f32_16x16x32_bf16 v[24:27], v[178:181], v[186:189], v[24:27]
	v_mfma_f32_16x16x32_bf16 v[16:19], v[174:177], v[190:193], v[16:19]
	v_mfma_f32_16x16x32_bf16 v[16:19], v[178:181], v[194:197], v[16:19]
	v_mfma_f32_16x16x32_bf16 v[20:23], v[166:169], v[190:193], v[20:23]
	v_mfma_f32_16x16x32_bf16 v[20:23], v[170:173], v[194:197], v[20:23]
	v_mfma_f32_16x16x32_bf16 v[80:83], v[150:153], v[190:193], v[80:83]
	v_mfma_f32_16x16x32_bf16 v[80:83], v[162:165], v[194:197], v[80:83]
	v_mfma_f32_16x16x32_bf16 v[84:87], v[128:131], v[190:193], v[84:87]
	v_mfma_f32_16x16x32_bf16 v[84:87], v[132:135], v[194:197], v[84:87]
	v_mfma_f32_16x16x32_bf16 v[76:79], v[128:131], v[198:201], v[76:79]
	v_mfma_f32_16x16x32_bf16 v[76:79], v[132:135], v[202:205], v[76:79]
	v_mfma_f32_16x16x32_bf16 v[72:75], v[150:153], v[198:201], v[72:75]
	v_mfma_f32_16x16x32_bf16 v[72:75], v[162:165], v[202:205], v[72:75]
	v_mfma_f32_16x16x32_bf16 v[12:15], v[166:169], v[198:201], v[12:15]
	v_mfma_f32_16x16x32_bf16 v[12:15], v[170:173], v[202:205], v[12:15]
	v_mfma_f32_16x16x32_bf16 v[8:11], v[174:177], v[198:201], v[8:11]
	v_mfma_f32_16x16x32_bf16 v[8:11], v[178:181], v[202:205], v[8:11]
	v_mfma_f32_16x16x32_bf16 v[0:3], v[174:177], v[206:209], v[0:3]
	v_mfma_f32_16x16x32_bf16 v[0:3], v[178:181], v[210:213], v[0:3]
	v_mfma_f32_16x16x32_bf16 v[4:7], v[166:169], v[206:209], v[4:7]
	v_mfma_f32_16x16x32_bf16 v[4:7], v[170:173], v[210:213], v[4:7]
	v_mfma_f32_16x16x32_bf16 v[56:59], v[150:153], v[206:209], v[56:59]
	v_mfma_f32_16x16x32_bf16 v[56:59], v[162:165], v[210:213], v[56:59]
	v_mfma_f32_16x16x32_bf16 v[60:63], v[128:131], v[206:209], v[60:63]
	v_mfma_f32_16x16x32_bf16 v[60:63], v[132:135], v[210:213], v[60:63]
	s_waitcnt vmcnt(8)
	s_barrier
; #define PG8_STAGE(bufoff, gbase, voff) do { _Pragma("unroll") for (int _i = 0; _i < 2; ++_i) \
;         __builtin_amdgcn_global_load_lds((const unsigned*)((const char*)(gbase) + (voff)[_i]), (PG8_LAS unsigned*)(lds + (bufoff) + ldsw + _i * 8192), 16, 0, 0); } while (0)
; #define PG8_LDA(dst, b, h) do { _Pragma("unroll") for (int m = 0; m < 4; ++m) _Pragma("unroll") for (int k = 0; k < 2; ++k) dst[m][k] = *(const PG8_LAS bf16x8*)(lds + PG8_SA(b, h) + aoff + m * 2048 + k * 1024); } while (0)
; #define PG8_WAIT_V(n) asm volatile("s_waitcnt vmcnt(" #n ")" ::: "memory")
; template <class Epi, class Sched, bool ALIGN_EPI = false, bool SP2 = false>
; __device__ __forceinline__ void gemm_phase(PG8_LAS unsigned char* lds, const Gemm g, const Sched& S, const Epi& E) {
;     ...
;         for (int t = 0; t < nt; t += 2) {
;             const bool last = (t == nt - 2);
;             const char* a1 = cA + (size_t)(t + 1) * kstep;
;             const char* a2 = last ? nA : cA + (size_t)(t + 2) * kstep; const char* b2 = last ? nB : cB + (size_t)(t + 2) * kstep;
;             const char* a3 = a2 + kstep; const char* b3 = b2 + kstep;
;             if (last && has_next) S.a_ready(nxt);
;             if constexpr (Epi::MIDK) { if (t == (nt >> 1)) { E.midk(acc, wr, fr); asm volatile("s_waitcnt lgkmcnt(0)" ::: "memory"); } }
;             if constexpr (SP2) {
;             PG8_LDB(B0, 0, 0); PG8_LDB(B1, 0, 1); PG8_SCHED; PG8_LDA(At, 0, 0); PG8_STAGE(PG8_SA(1, 1), a1 + hstep, voffA);
;             PG8_WAIT_V(8); PG8_WAIT_L(0); PG8_BAR; PG8_MMA(0, 0, At, B0); PG8_MMA(0, 1, At, B1); PG8_BAR; PG8_SCHED;
;             PG8_LDA(At, 0, 1); PG8_STAGE(PG8_SB(0, 0), b2, voffB); PG8_STAGE(PG8_SB(0, 1), b2 + hstep, voffB); PG8_STAGE(PG8_SA(0, 0), a2, voffA);
;             PG8_WAIT_V(8); PG8_WAIT_L(0); PG8_BAR; PG8_MMA(1, 0, At, B0); PG8_MMA(1, 1, At, B1); PG8_BAR; PG8_SCHED;
;             PG8_LDB(B0, 1, 0); PG8_LDB(B1, 1, 1); PG8_SCHED; PG8_LDA(At, 1, 0); PG8_STAGE(PG8_SA(0, 1), a2 + hstep, voffA);
;             PG8_WAIT_V(8); PG8_WAIT_L(0); PG8_BAR; PG8_MMA(0, 0, At, B0); PG8_MMA(0, 1, At, B1); PG8_BAR; PG8_SCHED;
;             PG8_LDA(At, 1, 1); PG8_STAGE(PG8_SB(1, 0), b3, voffB); PG8_STAGE(PG8_SB(1, 1), b3 + hstep, voffB); PG8_STAGE(PG8_SA(1, 0), a3, voffA);
;             PG8_WAIT_V(8); PG8_WAIT_L(0); PG8_BAR; PG8_MMA(1, 0, At, B0); PG8_MMA(1, 1, At, B1); PG8_BAR; PG8_SCHED;
	s_setprio 0
	ds_read_b128 v[128:131], v159
	ds_read_b128 v[132:135], v159 offset:1024
	ds_read_b128 v[150:153], v159 offset:2048
	ds_read_b128 v[162:165], v159 offset:3072
	ds_read_b128 v[166:169], v160
	ds_read_b128 v[170:173], v160 offset:1024
	ds_read_b128 v[174:177], v160 offset:2048
	ds_read_b128 v[178:181], v160 offset:3072
	ds_read_b128 v[182:185], v158 offset:32768
	ds_read_b128 v[186:189], v158 offset:33792
	ds_read_b128 v[190:193], v158 offset:34816
	ds_read_b128 v[194:197], v158 offset:35840
	ds_read_b128 v[198:201], v158 offset:36864
	ds_read_b128 v[202:205], v158 offset:37888
	ds_read_b128 v[206:209], v158 offset:38912
	ds_read_b128 v[210:213], v158 offset:39936
	s_add_u32 vcc_lo, s22, 0x404000
	s_addc_u32 vcc_hi, s23, 0
	s_add_i32 m0, s24, 0x4000
	s_nop 0
	global_load_lds_dwordx4 v136, vcc
	s_add_i32 m0, s24, 0x6000
	s_nop 0
	global_load_lds_dwordx4 v140, vcc
	s_waitcnt lgkmcnt(0)
	s_setprio 1
	v_mfma_f32_16x16x32_bf16 v[124:127], v[128:131], v[182:185], v[124:127]
	v_mfma_f32_16x16x32_bf16 v[124:127], v[132:135], v[186:189], v[124:127]
	v_mfma_f32_16x16x32_bf16 v[120:123], v[150:153], v[182:185], v[120:123]
	v_mfma_f32_16x16x32_bf16 v[120:123], v[162:165], v[186:189], v[120:123]
	v_mfma_f32_16x16x32_bf16 v[68:71], v[166:169], v[182:185], v[68:71]
	v_mfma_f32_16x16x32_bf16 v[68:71], v[170:173], v[186:189], v[68:71]
	v_mfma_f32_16x16x32_bf16 v[64:67], v[174:177], v[182:185], v[64:67]
	v_mfma_f32_16x16x32_bf16 v[64:67], v[178:181], v[186:189], v[64:67]
	v_mfma_f32_16x16x32_bf16 v[48:51], v[174:177], v[190:193], v[48:51]
	v_mfma_f32_16x16x32_bf16 v[48:51], v[178:181], v[194:197], v[48:51]
	v_mfma_f32_16x16x32_bf16 v[52:55], v[166:169], v[190:193], v[52:55]
	v_mfma_f32_16x16x32_bf16 v[52:55], v[170:173], v[194:197], v[52:55]
	v_mfma_f32_16x16x32_bf16 v[112:115], v[150:153], v[190:193], v[112:115]
	v_mfma_f32_16x16x32_bf16 v[112:115], v[162:165], v[194:197], v[112:115]
	v_mfma_f32_16x16x32_bf16 v[116:119], v[128:131], v[190:193], v[116:119]
	v_mfma_f32_16x16x32_bf16 v[116:119], v[132:135], v[194:197], v[116:119]
	v_mfma_f32_16x16x32_bf16 v[108:111], v[128:131], v[198:201], v[108:111]
	v_mfma_f32_16x16x32_bf16 v[108:111], v[132:135], v[202:205], v[108:111]
	v_mfma_f32_16x16x32_bf16 v[104:107], v[150:153], v[198:201], v[104:107]
	v_mfma_f32_16x16x32_bf16 v[104:107], v[162:165], v[202:205], v[104:107]
	v_mfma_f32_16x16x32_bf16 v[44:47], v[166:169], v[198:201], v[44:47]
	v_mfma_f32_16x16x32_bf16 v[44:47], v[170:173], v[202:205], v[44:47]
	v_mfma_f32_16x16x32_bf16 v[40:43], v[174:177], v[198:201], v[40:43]
	v_mfma_f32_16x16x32_bf16 v[40:43], v[178:181], v[202:205], v[40:43]
	v_mfma_f32_16x16x32_bf16 v[32:35], v[174:177], v[206:209], v[32:35]
	v_mfma_f32_16x16x32_bf16 v[32:35], v[178:181], v[210:213], v[32:35]
	v_mfma_f32_16x16x32_bf16 v[36:39], v[166:169], v[206:209], v[36:39]
	v_mfma_f32_16x16x32_bf16 v[36:39], v[170:173], v[210:213], v[36:39]
	v_mfma_f32_16x16x32_bf16 v[96:99], v[150:153], v[206:209], v[96:99]
	v_mfma_f32_16x16x32_bf16 v[96:99], v[162:165], v[210:213], v[96:99]
	v_mfma_f32_16x16x32_bf16 v[100:103], v[128:131], v[206:209], v[100:103]
	v_mfma_f32_16x16x32_bf16 v[100:103], v[132:135], v[210:213], v[100:103]
	s_waitcnt vmcnt(8)
	s_barrier
	s_setprio 0
	ds_read_b128 v[182:185], v158 offset:49152
	ds_read_b128 v[186:189], v158 offset:50176
	ds_read_b128 v[190:193], v158 offset:51200
	ds_read_b128 v[194:197], v158 offset:52224
	ds_read_b128 v[198:201], v158 offset:53248
	ds_read_b128 v[202:205], v158 offset:54272
	ds_read_b128 v[206:209], v158 offset:55296
	ds_read_b128 v[210:213], v158 offset:56320
	s_add_u32 s60, s20, 0x80
	s_addc_u32 s61, s21, 0
	s_add_u32 vcc_lo, s60, 0x404000
	s_addc_u32 vcc_hi, s61, 0
	s_add_i32 m0, s24, 0x18000
	s_nop 0
	global_load_lds_dwordx4 v138, s[60:61]
	s_add_i32 m0, s24, 0x1a000
	s_nop 0
	global_load_lds_dwordx4 v142, s[60:61]
	s_add_i32 m0, s24, 0x1c000
	s_nop 0
	global_load_lds_dwordx4 v138, vcc
	s_add_i32 m0, s24, 0x1e000
	s_nop 0
	global_load_lds_dwordx4 v142, vcc
	s_add_u32 s60, s22, 0x80
	s_addc_u32 s61, s23, 0
	s_add_i32 m0, s24, 0x8000
	s_nop 0
	global_load_lds_dwordx4 v136, s[60:61]
	s_add_i32 m0, s24, 0xa000
	s_nop 0
	global_load_lds_dwordx4 v140, s[60:61]
	s_waitcnt lgkmcnt(0)
	s_setprio 1
	v_mfma_f32_16x16x32_bf16 v[92:95], v[128:131], v[182:185], v[92:95]
	v_mfma_f32_16x16x32_bf16 v[92:95], v[132:135], v[186:189], v[92:95]
	v_mfma_f32_16x16x32_bf16 v[88:91], v[150:153], v[182:185], v[88:91]
	v_mfma_f32_16x16x32_bf16 v[88:91], v[162:165], v[186:189], v[88:91]
	v_mfma_f32_16x16x32_bf16 v[28:31], v[166:169], v[182:185], v[28:31]
	v_mfma_f32_16x16x32_bf16 v[28:31], v[170:173], v[186:189], v[28:31]
	v_mfma_f32_16x16x32_bf16 v[24:27], v[174:177], v[182:185], v[24:27]
	v_mfma_f32_16x16x32_bf16 v[24:27], v[178:181], v[186:189], v[24:27]
	v_mfma_f32_16x16x32_bf16 v[16:19], v[174:177], v[190:193], v[16:19]
	v_mfma_f32_16x16x32_bf16 v[16:19], v[178:181], v[194:197], v[16:19]
	v_mfma_f32_16x16x32_bf16 v[20:23], v[166:169], v[190:193], v[20:23]
	v_mfma_f32_16x16x32_bf16 v[20:23], v[170:173], v[194:197], v[20:23]
	v_mfma_f32_16x16x32_bf16 v[80:83], v[150:153], v[190:193], v[80:83]
	v_mfma_f32_16x16x32_bf16 v[80:83], v[162:165], v[194:197], v[80:83]
	v_mfma_f32_16x16x32_bf16 v[84:87], v[128:131], v[190:193], v[84:87]
	v_mfma_f32_16x16x32_bf16 v[84:87], v[132:135], v[194:197], v[84:87]
	v_mfma_f32_16x16x32_bf16 v[76:79], v[128:131], v[198:201], v[76:79]
	v_mfma_f32_16x16x32_bf16 v[76:79], v[132:135], v[202:205], v[76:79]
	v_mfma_f32_16x16x32_bf16 v[72:75], v[150:153], v[198:201], v[72:75]
	v_mfma_f32_16x16x32_bf16 v[72:75], v[162:165], v[202:205], v[72:75]
	v_mfma_f32_16x16x32_bf16 v[12:15], v[166:169], v[198:201], v[12:15]
	v_mfma_f32_16x16x32_bf16 v[12:15], v[170:173], v[202:205], v[12:15]
	v_mfma_f32_16x16x32_bf16 v[8:11], v[174:177], v[198:201], v[8:11]
	v_mfma_f32_16x16x32_bf16 v[8:11], v[178:181], v[202:205], v[8:11]
	v_mfma_f32_16x16x32_bf16 v[0:3], v[174:177], v[206:209], v[0:3]
	v_mfma_f32_16x16x32_bf16 v[0:3], v[178:181], v[210:213], v[0:3]
	v_mfma_f32_16x16x32_bf16 v[4:7], v[166:169], v[206:209], v[4:7]
	v_mfma_f32_16x16x32_bf16 v[4:7], v[170:173], v[210:213], v[4:7]
	v_mfma_f32_16x16x32_bf16 v[56:59], v[150:153], v[206:209], v[56:59]
	v_mfma_f32_16x16x32_bf16 v[56:59], v[162:165], v[210:213], v[56:59]
	v_mfma_f32_16x16x32_bf16 v[60:63], v[128:131], v[206:209], v[60:63]
	v_mfma_f32_16x16x32_bf16 v[60:63], v[132:135], v[210:213], v[60:63]
	s_waitcnt vmcnt(8)
	s_barrier
	s_setprio 0
	s_add_i32 s59, s59, 2
	s_add_u32 s18, s18, 0x100
	s_addc_u32 s19, s19, 0
	s_add_u32 s57, s57, 0x100
	s_addc_u32 s58, s58, 0
	s_cmpk_gt_u32 s59, 0xfd
	s_cbranch_scc0 .LBB0_1321
	s_branch .Lf2_exit
; #define PG8_STAGE(bufoff, gbase, voff) do { _Pragma("unroll") for (int _i = 0; _i < 2; ++_i) \
;         __builtin_amdgcn_global_load_lds((const unsigned*)((const char*)(gbase) + (voff)[_i]), (PG8_LAS unsigned*)(lds + (bufoff) + ldsw + _i * 8192), 16, 0, 0); } while (0)
; #define PG8_LDA(dst, b, h) do { _Pragma("unroll") for (int m = 0; m < 4; ++m) _Pragma("unroll") for (int k = 0; k < 2; ++k) dst[m][k] = *(const PG8_LAS bf16x8*)(lds + PG8_SA(b, h) + aoff + m * 2048 + k * 1024); } while (0)
; #define PG8_LDB(dst, b, h) do { _Pragma("unroll") for (int n = 0; n < 2; ++n) _Pragma("unroll") for (int k = 0; k < 2; ++k) dst[n][k] = *(const PG8_LAS bf16x8*)(lds + PG8_SB(b, h) + boff + n * 2048 + k * 1024); } while (0)
; #define PG8_MMA(ai, bj, At, Bt) do { __builtin_amdgcn_s_setprio(1); _Pragma("unroll") for (int m = 0; m < 4; ++m) _Pragma("unroll") for (int n = 0; n < 2; ++n) _Pragma("unroll") for (int k = 0; k < 2; ++k) \
;         acc[ai][bj][m][n] = __builtin_amdgcn_mfma_f32_16x16x32_bf16(Bt[n][k], At[m][k], acc[ai][bj][m][n], 0, 0, 0); __builtin_amdgcn_s_setprio(0); } while (0)
; template <class Epi, class Sched, bool ALIGN_EPI = false, bool SP2 = false>
; __device__ __forceinline__ void gemm_phase(PG8_LAS unsigned char* lds, const Gemm g, const Sched& S, const Epi& E) {
;     ...
;         for (int t = 0; t < nt; t += 2) {
;             const bool last = (t == nt - 2);
;             const char* a1 = cA + (size_t)(t + 1) * kstep;
;             const char* a2 = last ? nA : cA + (size_t)(t + 2) * kstep; const char* b2 = last ? nB : cB + (size_t)(t + 2) * kstep;
;             const char* a3 = a2 + kstep; const char* b3 = b2 + kstep;
;             if (last && has_next) S.a_ready(nxt);
;             if constexpr (Epi::MIDK) { if (t == (nt >> 1)) { E.midk(acc, wr, fr); asm volatile("s_waitcnt lgkmcnt(0)" ::: "memory"); } }
;             if constexpr (SP2) {
;             PG8_LDB(B0, 0, 0); PG8_LDB(B1, 0, 1); PG8_SCHED; PG8_LDA(At, 0, 0); PG8_STAGE(PG8_SA(1, 1), a1 + hstep, voffA);
;             PG8_WAIT_V(8); PG8_WAIT_L(0); PG8_BAR; PG8_MMA(0, 0, At, B0); PG8_MMA(0, 1, At, B1); PG8_BAR; PG8_SCHED;
;             PG8_LDA(At, 0, 1); PG8_STAGE(PG8_SB(0, 0), b2, voffB); PG8_STAGE(PG8_SB(0, 1), b2 + hstep, voffB); PG8_STAGE(PG8_SA(0, 0), a2, voffA);
;             PG8_WAIT_V(8); PG8_WAIT_L(0); PG8_BAR; PG8_MMA(1, 0, At, B0); PG8_MMA(1, 1, At, B1); PG8_BAR; PG8_SCHED;
.Lf2_h1:
	ds_read_b128 v[128:131], v156
	ds_read_b128 v[132:135], v156 offset:1024
	ds_read_b128 v[150:153], v156 offset:2048
	ds_read_b128 v[162:165], v156 offset:3072
	ds_read_b128 v[166:169], v157
	ds_read_b128 v[170:173], v157 offset:1024
	ds_read_b128 v[174:177], v157 offset:2048
	ds_read_b128 v[178:181], v157 offset:3072
	s_add_u32 s20, s18, 0xffbfc080
	s_addc_u32 s21, s19, -1
	s_cmpk_eq_i32 s59, 0xfc
	s_cselect_b32 s23, s7, s21
	s_cselect_b32 s22, s6, s20
	s_cselect_b32 s21, s17, s58
	s_cselect_b32 s20, s16, s57
	ds_read_b128 v[182:185], v158
	ds_read_b128 v[186:189], v158 offset:1024
	ds_read_b128 v[190:193], v158 offset:2048
	ds_read_b128 v[194:197], v158 offset:3072
	ds_read_b128 v[198:201], v158 offset:4096
	ds_read_b128 v[202:205], v158 offset:5120
	ds_read_b128 v[206:209], v158 offset:6144
	ds_read_b128 v[210:213], v158 offset:7168
	s_add_i32 m0, s24, 0xc000
	s_nop 0
	global_load_lds_dwordx4 v136, s[18:19]
	s_add_i32 m0, s24, 0xe000
	s_nop 0
	global_load_lds_dwordx4 v140, s[18:19]
	s_sleep 2
	s_waitcnt lgkmcnt(0)
	s_setprio 2
	s_waitcnt vmcnt(8)
	s_barrier
	v_mfma_f32_16x16x32_bf16 v[124:127], v[128:131], v[182:185], v[124:127]
	v_mfma_f32_16x16x32_bf16 v[124:127], v[132:135], v[186:189], v[124:127]
	v_mfma_f32_16x16x32_bf16 v[120:123], v[150:153], v[182:185], v[120:123]
	v_mfma_f32_16x16x32_bf16 v[120:123], v[162:165], v[186:189], v[120:123]
	v_mfma_f32_16x16x32_bf16 v[68:71], v[166:169], v[182:185], v[68:71]
	v_mfma_f32_16x16x32_bf16 v[68:71], v[170:173], v[186:189], v[68:71]
	v_mfma_f32_16x16x32_bf16 v[64:67], v[174:177], v[182:185], v[64:67]
	v_mfma_f32_16x16x32_bf16 v[64:67], v[178:181], v[186:189], v[64:67]
	v_mfma_f32_16x16x32_bf16 v[48:51], v[174:177], v[190:193], v[48:51]
	v_mfma_f32_16x16x32_bf16 v[48:51], v[178:181], v[194:197], v[48:51]
	v_mfma_f32_16x16x32_bf16 v[52:55], v[166:169], v[190:193], v[52:55]
	v_mfma_f32_16x16x32_bf16 v[52:55], v[170:173], v[194:197], v[52:55]
	v_mfma_f32_16x16x32_bf16 v[112:115], v[150:153], v[190:193], v[112:115]
	v_mfma_f32_16x16x32_bf16 v[112:115], v[162:165], v[194:197], v[112:115]
	v_mfma_f32_16x16x32_bf16 v[116:119], v[128:131], v[190:193], v[116:119]
	v_mfma_f32_16x16x32_bf16 v[116:119], v[132:135], v[194:197], v[116:119]
	v_mfma_f32_16x16x32_bf16 v[108:111], v[128:131], v[198:201], v[108:111]
	v_mfma_f32_16x16x32_bf16 v[108:111], v[132:135], v[202:205], v[108:111]
	v_mfma_f32_16x16x32_bf16 v[104:107], v[150:153], v[198:201], v[104:107]
	v_mfma_f32_16x16x32_bf16 v[104:107], v[162:165], v[202:205], v[104:107]
	v_mfma_f32_16x16x32_bf16 v[44:47], v[166:169], v[198:201], v[44:47]
	v_mfma_f32_16x16x32_bf16 v[44:47], v[170:173], v[202:205], v[44:47]
	v_mfma_f32_16x16x32_bf16 v[40:43], v[174:177], v[198:201], v[40:43]
	v_mfma_f32_16x16x32_bf16 v[40:43], v[178:181], v[202:205], v[40:43]
	v_mfma_f32_16x16x32_bf16 v[32:35], v[174:177], v[206:209], v[32:35]
	v_mfma_f32_16x16x32_bf16 v[32:35], v[178:181], v[210:213], v[32:35]
	v_mfma_f32_16x16x32_bf16 v[36:39], v[166:169], v[206:209], v[36:39]
	v_mfma_f32_16x16x32_bf16 v[36:39], v[170:173], v[210:213], v[36:39]
	v_mfma_f32_16x16x32_bf16 v[96:99], v[150:153], v[206:209], v[96:99]
	v_mfma_f32_16x16x32_bf16 v[96:99], v[162:165], v[210:213], v[96:99]
	v_mfma_f32_16x16x32_bf16 v[100:103], v[128:131], v[206:209], v[100:103]
	v_mfma_f32_16x16x32_bf16 v[100:103], v[132:135], v[210:213], v[100:103]
	s_setprio 0
	ds_read_b128 v[182:185], v158 offset:16384
	ds_read_b128 v[186:189], v158 offset:17408
	ds_read_b128 v[190:193], v158 offset:18432
	ds_read_b128 v[194:197], v158 offset:19456
	ds_read_b128 v[198:201], v158 offset:20480
	ds_read_b128 v[202:205], v158 offset:21504
	ds_read_b128 v[206:209], v158 offset:22528
	ds_read_b128 v[210:213], v158 offset:23552
	s_add_u32 vcc_lo, s20, 0x404000
	s_addc_u32 vcc_hi, s21, 0
	s_add_i32 m0, s24, 0x10000
	s_nop 0
	global_load_lds_dwordx4 v138, s[20:21]
	s_add_i32 m0, s24, 0x12000
	s_nop 0
	global_load_lds_dwordx4 v142, s[20:21]
	s_add_i32 m0, s24, 0x14000
	s_nop 0
	global_load_lds_dwordx4 v138, vcc
	s_add_i32 m0, s24, 0x16000
	s_nop 0
	global_load_lds_dwordx4 v142, vcc
	s_mov_b32 m0, s24
	s_nop 0
	global_load_lds_dwordx4 v136, s[22:23]
	s_add_i32 m0, s24, 0x2000
	s_nop 0
	global_load_lds_dwordx4 v140, s[22:23]
	s_sleep 2
	s_waitcnt lgkmcnt(0)
	s_setprio 2
	s_waitcnt vmcnt(8)
	s_barrier
; #define PG8_STAGE(bufoff, gbase, voff) do { _Pragma("unroll") for (int _i = 0; _i < 2; ++_i) \
;         __builtin_amdgcn_global_load_lds((const unsigned*)((const char*)(gbase) + (voff)[_i]), (PG8_LAS unsigned*)(lds + (bufoff) + ldsw + _i * 8192), 16, 0, 0); } while (0)
; #define PG8_LDA(dst, b, h) do { _Pragma("unroll") for (int m = 0; m < 4; ++m) _Pragma("unroll") for (int k = 0; k < 2; ++k) dst[m][k] = *(const PG8_LAS bf16x8*)(lds + PG8_SA(b, h) + aoff + m * 2048 + k * 1024); } while (0)
; #define PG8_LDB(dst, b, h) do { _Pragma("unroll") for (int n = 0; n < 2; ++n) _Pragma("unroll") for (int k = 0; k < 2; ++k) dst[n][k] = *(const PG8_LAS bf16x8*)(lds + PG8_SB(b, h) + boff + n * 2048 + k * 1024); } while (0)
; #define PG8_MMA(ai, bj, At, Bt) do { __builtin_amdgcn_s_setprio(1); _Pragma("unroll") for (int m = 0; m < 4; ++m) _Pragma("unroll") for (int n = 0; n < 2; ++n) _Pragma("unroll") for (int k = 0; k < 2; ++k) \
;         acc[ai][bj][m][n] = __builtin_amdgcn_mfma_f32_16x16x32_bf16(Bt[n][k], At[m][k], acc[ai][bj][m][n], 0, 0, 0); __builtin_amdgcn_s_setprio(0); } while (0)
; #define PG8_WAIT_V(n) asm volatile("s_waitcnt vmcnt(" #n ")" ::: "memory")
; #define PG8_WAIT_L(n) asm volatile("s_waitcnt lgkmcnt(" #n ")" ::: "memory")
; #define PG8_BAR __builtin_amdgcn_s_barrier()
; #define PG8_SCHED __builtin_amdgcn_sched_barrier(0)
; template <class Epi, class Sched, bool ALIGN_EPI = false, bool SP2 = false>
; __device__ __forceinline__ void gemm_phase(PG8_LAS unsigned char* lds, const Gemm g, const Sched& S, const Epi& E) {
;     ...
;             PG8_WAIT_V(8); PG8_WAIT_L(0); PG8_BAR; PG8_MMA(1, 0, At, B0); PG8_MMA(1, 1, At, B1); PG8_BAR; PG8_SCHED;
;             PG8_LDB(B0, 1, 0); PG8_LDB(B1, 1, 1); PG8_SCHED; PG8_LDA(At, 1, 0); PG8_STAGE(PG8_SA(0, 1), a2 + hstep, voffA);
;             PG8_WAIT_V(8); PG8_WAIT_L(0); PG8_BAR; PG8_MMA(0, 0, At, B0); PG8_MMA(0, 1, At, B1); PG8_BAR; PG8_SCHED;
	v_mfma_f32_16x16x32_bf16 v[92:95], v[128:131], v[182:185], v[92:95]
	v_mfma_f32_16x16x32_bf16 v[92:95], v[132:135], v[186:189], v[92:95]
	v_mfma_f32_16x16x32_bf16 v[88:91], v[150:153], v[182:185], v[88:91]
	v_mfma_f32_16x16x32_bf16 v[88:91], v[162:165], v[186:189], v[88:91]
	v_mfma_f32_16x16x32_bf16 v[28:31], v[166:169], v[182:185], v[28:31]
	v_mfma_f32_16x16x32_bf16 v[28:31], v[170:173], v[186:189], v[28:31]
	v_mfma_f32_16x16x32_bf16 v[24:27], v[174:177], v[182:185], v[24:27]
	v_mfma_f32_16x16x32_bf16 v[24:27], v[178:181], v[186:189], v[24:27]
	v_mfma_f32_16x16x32_bf16 v[16:19], v[174:177], v[190:193], v[16:19]
	v_mfma_f32_16x16x32_bf16 v[16:19], v[178:181], v[194:197], v[16:19]
	v_mfma_f32_16x16x32_bf16 v[20:23], v[166:169], v[190:193], v[20:23]
	v_mfma_f32_16x16x32_bf16 v[20:23], v[170:173], v[194:197], v[20:23]
	v_mfma_f32_16x16x32_bf16 v[80:83], v[150:153], v[190:193], v[80:83]
	v_mfma_f32_16x16x32_bf16 v[80:83], v[162:165], v[194:197], v[80:83]
	v_mfma_f32_16x16x32_bf16 v[84:87], v[128:131], v[190:193], v[84:87]
	v_mfma_f32_16x16x32_bf16 v[84:87], v[132:135], v[194:197], v[84:87]
	v_mfma_f32_16x16x32_bf16 v[76:79], v[128:131], v[198:201], v[76:79]
	v_mfma_f32_16x16x32_bf16 v[76:79], v[132:135], v[202:205], v[76:79]
	v_mfma_f32_16x16x32_bf16 v[72:75], v[150:153], v[198:201], v[72:75]
	v_mfma_f32_16x16x32_bf16 v[72:75], v[162:165], v[202:205], v[72:75]
	v_mfma_f32_16x16x32_bf16 v[12:15], v[166:169], v[198:201], v[12:15]
	v_mfma_f32_16x16x32_bf16 v[12:15], v[170:173], v[202:205], v[12:15]
	v_mfma_f32_16x16x32_bf16 v[8:11], v[174:177], v[198:201], v[8:11]
	v_mfma_f32_16x16x32_bf16 v[8:11], v[178:181], v[202:205], v[8:11]
	v_mfma_f32_16x16x32_bf16 v[0:3], v[174:177], v[206:209], v[0:3]
	v_mfma_f32_16x16x32_bf16 v[0:3], v[178:181], v[210:213], v[0:3]
	v_mfma_f32_16x16x32_bf16 v[4:7], v[166:169], v[206:209], v[4:7]
	v_mfma_f32_16x16x32_bf16 v[4:7], v[170:173], v[210:213], v[4:7]
	v_mfma_f32_16x16x32_bf16 v[56:59], v[150:153], v[206:209], v[56:59]
	v_mfma_f32_16x16x32_bf16 v[56:59], v[162:165], v[210:213], v[56:59]
	v_mfma_f32_16x16x32_bf16 v[60:63], v[128:131], v[206:209], v[60:63]
	v_mfma_f32_16x16x32_bf16 v[60:63], v[132:135], v[210:213], v[60:63]
	s_setprio 0
	ds_read_b128 v[128:131], v159
	ds_read_b128 v[132:135], v159 offset:1024
	ds_read_b128 v[150:153], v159 offset:2048
	ds_read_b128 v[162:165], v159 offset:3072
	ds_read_b128 v[166:169], v160
	ds_read_b128 v[170:173], v160 offset:1024
	ds_read_b128 v[174:177], v160 offset:2048
	ds_read_b128 v[178:181], v160 offset:3072
	ds_read_b128 v[182:185], v158 offset:32768
	ds_read_b128 v[186:189], v158 offset:33792
	ds_read_b128 v[190:193], v158 offset:34816
	ds_read_b128 v[194:197], v158 offset:35840
	ds_read_b128 v[198:201], v158 offset:36864
	ds_read_b128 v[202:205], v158 offset:37888
	ds_read_b128 v[206:209], v158 offset:38912
	ds_read_b128 v[210:213], v158 offset:39936
	s_add_u32 vcc_lo, s22, 0x404000
	s_addc_u32 vcc_hi, s23, 0
	s_add_i32 m0, s24, 0x4000
	s_nop 0
	global_load_lds_dwordx4 v136, vcc
	s_add_i32 m0, s24, 0x6000
	s_nop 0
	global_load_lds_dwordx4 v140, vcc
	s_sleep 2
	s_waitcnt lgkmcnt(0)
	s_setprio 2
	s_waitcnt vmcnt(8)
	s_barrier
; #define PG8_STAGE(bufoff, gbase, voff) do { _Pragma("unroll") for (int _i = 0; _i < 2; ++_i) \
;         __builtin_amdgcn_global_load_lds((const unsigned*)((const char*)(gbase) + (voff)[_i]), (PG8_LAS unsigned*)(lds + (bufoff) + ldsw + _i * 8192), 16, 0, 0); } while (0)
; #define PG8_LDA(dst, b, h) do { _Pragma("unroll") for (int m = 0; m < 4; ++m) _Pragma("unroll") for (int k = 0; k < 2; ++k) dst[m][k] = *(const PG8_LAS bf16x8*)(lds + PG8_SA(b, h) + aoff + m * 2048 + k * 1024); } while (0)
; #define PG8_LDB(dst, b, h) do { _Pragma("unroll") for (int n = 0; n < 2; ++n) _Pragma("unroll") for (int k = 0; k < 2; ++k) dst[n][k] = *(const PG8_LAS bf16x8*)(lds + PG8_SB(b, h) + boff + n * 2048 + k * 1024); } while (0)
; #define PG8_MMA(ai, bj, At, Bt) do { __builtin_amdgcn_s_setprio(1); _Pragma("unroll") for (int m = 0; m < 4; ++m) _Pragma("unroll") for (int n = 0; n < 2; ++n) _Pragma("unroll") for (int k = 0; k < 2; ++k) \
;         acc[ai][bj][m][n] = __builtin_amdgcn_mfma_f32_16x16x32_bf16(Bt[n][k], At[m][k], acc[ai][bj][m][n], 0, 0, 0); __builtin_amdgcn_s_setprio(0); } while (0)
; #define PG8_WAIT_V(n) asm volatile("s_waitcnt vmcnt(" #n ")" ::: "memory")
; #define PG8_WAIT_L(n) asm volatile("s_waitcnt lgkmcnt(" #n ")" ::: "memory")
; #define PG8_BAR __builtin_amdgcn_s_barrier()
; template <class Epi, class Sched, bool ALIGN_EPI = false, bool SP2 = false>
; __device__ __forceinline__ void gemm_phase(PG8_LAS unsigned char* lds, const Gemm g, const Sched& S, const Epi& E) {
;     ...
;         for (int t = 0; t < nt; t += 2) {
;             const bool last = (t == nt - 2);
;             const char* a1 = cA + (size_t)(t + 1) * kstep;
;             const char* a2 = last ? nA : cA + (size_t)(t + 2) * kstep; const char* b2 = last ? nB : cB + (size_t)(t + 2) * kstep;
;             const char* a3 = a2 + kstep; const char* b3 = b2 + kstep;
;     ...
;             PG8_LDB(B0, 1, 0); PG8_LDB(B1, 1, 1); PG8_SCHED; PG8_LDA(At, 1, 0); PG8_STAGE(PG8_SA(0, 1), a2 + hstep, voffA);
;             PG8_WAIT_V(8); PG8_WAIT_L(0); PG8_BAR; PG8_MMA(0, 0, At, B0); PG8_MMA(0, 1, At, B1); PG8_BAR; PG8_SCHED;
;             PG8_LDA(At, 1, 1); PG8_STAGE(PG8_SB(1, 0), b3, voffB); PG8_STAGE(PG8_SB(1, 1), b3 + hstep, voffB); PG8_STAGE(PG8_SA(1, 0), a3, voffA);
;             PG8_WAIT_V(8); PG8_WAIT_L(0); PG8_BAR; PG8_MMA(1, 0, At, B0); PG8_MMA(1, 1, At, B1); PG8_BAR; PG8_SCHED;
	v_mfma_f32_16x16x32_bf16 v[124:127], v[128:131], v[182:185], v[124:127]
	v_mfma_f32_16x16x32_bf16 v[124:127], v[132:135], v[186:189], v[124:127]
	v_mfma_f32_16x16x32_bf16 v[120:123], v[150:153], v[182:185], v[120:123]
	v_mfma_f32_16x16x32_bf16 v[120:123], v[162:165], v[186:189], v[120:123]
	v_mfma_f32_16x16x32_bf16 v[68:71], v[166:169], v[182:185], v[68:71]
	v_mfma_f32_16x16x32_bf16 v[68:71], v[170:173], v[186:189], v[68:71]
	v_mfma_f32_16x16x32_bf16 v[64:67], v[174:177], v[182:185], v[64:67]
	v_mfma_f32_16x16x32_bf16 v[64:67], v[178:181], v[186:189], v[64:67]
	v_mfma_f32_16x16x32_bf16 v[48:51], v[174:177], v[190:193], v[48:51]
	v_mfma_f32_16x16x32_bf16 v[48:51], v[178:181], v[194:197], v[48:51]
	v_mfma_f32_16x16x32_bf16 v[52:55], v[166:169], v[190:193], v[52:55]
	v_mfma_f32_16x16x32_bf16 v[52:55], v[170:173], v[194:197], v[52:55]
	v_mfma_f32_16x16x32_bf16 v[112:115], v[150:153], v[190:193], v[112:115]
	v_mfma_f32_16x16x32_bf16 v[112:115], v[162:165], v[194:197], v[112:115]
	v_mfma_f32_16x16x32_bf16 v[116:119], v[128:131], v[190:193], v[116:119]
	v_mfma_f32_16x16x32_bf16 v[116:119], v[132:135], v[194:197], v[116:119]
	v_mfma_f32_16x16x32_bf16 v[108:111], v[128:131], v[198:201], v[108:111]
	v_mfma_f32_16x16x32_bf16 v[108:111], v[132:135], v[202:205], v[108:111]
	v_mfma_f32_16x16x32_bf16 v[104:107], v[150:153], v[198:201], v[104:107]
	v_mfma_f32_16x16x32_bf16 v[104:107], v[162:165], v[202:205], v[104:107]
	v_mfma_f32_16x16x32_bf16 v[44:47], v[166:169], v[198:201], v[44:47]
	v_mfma_f32_16x16x32_bf16 v[44:47], v[170:173], v[202:205], v[44:47]
	v_mfma_f32_16x16x32_bf16 v[40:43], v[174:177], v[198:201], v[40:43]
	v_mfma_f32_16x16x32_bf16 v[40:43], v[178:181], v[202:205], v[40:43]
	v_mfma_f32_16x16x32_bf16 v[32:35], v[174:177], v[206:209], v[32:35]
	v_mfma_f32_16x16x32_bf16 v[32:35], v[178:181], v[210:213], v[32:35]
	v_mfma_f32_16x16x32_bf16 v[36:39], v[166:169], v[206:209], v[36:39]
	v_mfma_f32_16x16x32_bf16 v[36:39], v[170:173], v[210:213], v[36:39]
	v_mfma_f32_16x16x32_bf16 v[96:99], v[150:153], v[206:209], v[96:99]
	v_mfma_f32_16x16x32_bf16 v[96:99], v[162:165], v[210:213], v[96:99]
	v_mfma_f32_16x16x32_bf16 v[100:103], v[128:131], v[206:209], v[100:103]
	v_mfma_f32_16x16x32_bf16 v[100:103], v[132:135], v[210:213], v[100:103]
	s_setprio 0
	ds_read_b128 v[182:185], v158 offset:49152
	ds_read_b128 v[186:189], v158 offset:50176
	ds_read_b128 v[190:193], v158 offset:51200
	ds_read_b128 v[194:197], v158 offset:52224
	ds_read_b128 v[198:201], v158 offset:53248
	ds_read_b128 v[202:205], v158 offset:54272
	ds_read_b128 v[206:209], v158 offset:55296
	ds_read_b128 v[210:213], v158 offset:56320
	s_add_u32 s60, s20, 0x80
	s_addc_u32 s61, s21, 0
	s_add_u32 vcc_lo, s60, 0x404000
	s_addc_u32 vcc_hi, s61, 0
	s_add_i32 m0, s24, 0x18000
	s_nop 0
	global_load_lds_dwordx4 v138, s[60:61]
	s_add_i32 m0, s24, 0x1a000
	s_nop 0
	global_load_lds_dwordx4 v142, s[60:61]
	s_add_i32 m0, s24, 0x1c000
	s_nop 0
	global_load_lds_dwordx4 v138, vcc
	s_add_i32 m0, s24, 0x1e000
	s_nop 0
	global_load_lds_dwordx4 v142, vcc
	s_add_u32 s60, s22, 0x80
	s_addc_u32 s61, s23, 0
	s_add_i32 m0, s24, 0x8000
	s_nop 0
	global_load_lds_dwordx4 v136, s[60:61]
	s_add_i32 m0, s24, 0xa000
	s_nop 0
	global_load_lds_dwordx4 v140, s[60:61]
	s_sleep 2
	s_waitcnt lgkmcnt(0)
	s_setprio 2
	s_waitcnt vmcnt(8)
	s_barrier
	v_mfma_f32_16x16x32_bf16 v[92:95], v[128:131], v[182:185], v[92:95]
	v_mfma_f32_16x16x32_bf16 v[92:95], v[132:135], v[186:189], v[92:95]
	v_mfma_f32_16x16x32_bf16 v[88:91], v[150:153], v[182:185], v[88:91]
	v_mfma_f32_16x16x32_bf16 v[88:91], v[162:165], v[186:189], v[88:91]
	v_mfma_f32_16x16x32_bf16 v[28:31], v[166:169], v[182:185], v[28:31]
	v_mfma_f32_16x16x32_bf16 v[28:31], v[170:173], v[186:189], v[28:31]
	v_mfma_f32_16x16x32_bf16 v[24:27], v[174:177], v[182:185], v[24:27]
	v_mfma_f32_16x16x32_bf16 v[24:27], v[178:181], v[186:189], v[24:27]
	v_mfma_f32_16x16x32_bf16 v[16:19], v[174:177], v[190:193], v[16:19]
	v_mfma_f32_16x16x32_bf16 v[16:19], v[178:181], v[194:197], v[16:19]
	v_mfma_f32_16x16x32_bf16 v[20:23], v[166:169], v[190:193], v[20:23]
	v_mfma_f32_16x16x32_bf16 v[20:23], v[170:173], v[194:197], v[20:23]
	v_mfma_f32_16x16x32_bf16 v[80:83], v[150:153], v[190:193], v[80:83]
	v_mfma_f32_16x16x32_bf16 v[80:83], v[162:165], v[194:197], v[80:83]
	v_mfma_f32_16x16x32_bf16 v[84:87], v[128:131], v[190:193], v[84:87]
	v_mfma_f32_16x16x32_bf16 v[84:87], v[132:135], v[194:197], v[84:87]
	v_mfma_f32_16x16x32_bf16 v[76:79], v[128:131], v[198:201], v[76:79]
	v_mfma_f32_16x16x32_bf16 v[76:79], v[132:135], v[202:205], v[76:79]
	v_mfma_f32_16x16x32_bf16 v[72:75], v[150:153], v[198:201], v[72:75]
	v_mfma_f32_16x16x32_bf16 v[72:75], v[162:165], v[202:205], v[72:75]
	v_mfma_f32_16x16x32_bf16 v[12:15], v[166:169], v[198:201], v[12:15]
	v_mfma_f32_16x16x32_bf16 v[12:15], v[170:173], v[202:205], v[12:15]
	v_mfma_f32_16x16x32_bf16 v[8:11], v[174:177], v[198:201], v[8:11]
	v_mfma_f32_16x16x32_bf16 v[8:11], v[178:181], v[202:205], v[8:11]
	v_mfma_f32_16x16x32_bf16 v[0:3], v[174:177], v[206:209], v[0:3]
	v_mfma_f32_16x16x32_bf16 v[0:3], v[178:181], v[210:213], v[0:3]
	v_mfma_f32_16x16x32_bf16 v[4:7], v[166:169], v[206:209], v[4:7]
	v_mfma_f32_16x16x32_bf16 v[4:7], v[170:173], v[210:213], v[4:7]
	v_mfma_f32_16x16x32_bf16 v[56:59], v[150:153], v[206:209], v[56:59]
	v_mfma_f32_16x16x32_bf16 v[56:59], v[162:165], v[210:213], v[56:59]
	v_mfma_f32_16x16x32_bf16 v[60:63], v[128:131], v[206:209], v[60:63]
	v_mfma_f32_16x16x32_bf16 v[60:63], v[132:135], v[210:213], v[60:63]
	s_setprio 0
	s_add_i32 s59, s59, 2
	s_add_u32 s18, s18, 0x100
	s_addc_u32 s19, s19, 0
	s_add_u32 s57, s57, 0x100
	s_addc_u32 s58, s58, 0
	s_cmpk_gt_u32 s59, 0xfd
	s_cbranch_scc0 .Lf2_h1
